# late weight transposes moved from phase 0 into the idle tail of phase 2 (224 WGs), no in-proj stagger
# baseline (speedup 1.0000x reference)
.LBB0_75:
	s_or_b64 exec, exec, s[0:1]
	v_mov_b32_e32 v1, v202
	s_mov_b32 s0, s74
	s_barrier
	s_nop 0
	v_ashrrev_i32_e32 v2, 6, v1
	s_sub_i32 s0, s0, 0xc0
	s_cmp_lt_i32 s0, 0
	s_cselect_b32 s0, 0x7000, s0
	v_lshl_add_u32 v3, v2, 12, s0
	s_movk_i32 s0, 16
	v_cmp_gt_i32_e32 vcc, s0, v3
	s_and_saveexec_b64 s[0:1], vcc
	s_cbranch_execz .LBB0_170
	s_movk_i32 s2, 0x2100
	v_add_u32_e32 v5, 0x980, v3
	v_mul_lo_u32 v3, v2, s2
	v_and_b32_e32 v46, 31, v1
	v_bfe_u32 v2, v1, 5, 1
	v_bfe_u32 v47, v1, 3, 3
	v_lshlrev_b32_e32 v1, 3, v1
	v_and_b32_e32 v1, 56, v1
	v_readlane_b32 s8, v253, 2
	v_lshlrev_b32_e32 v6, 1, v1
	v_mov_b32_e32 v7, 0
	v_readlane_b32 s9, v253, 3
	s_mov_b64 s[2:3], 0x2080000
	v_add_u32_e32 v10, 0, v3
	v_lshl_add_u64 v[26:27], s[8:9], 0, v[6:7]
	v_lshlrev_b32_e32 v28, 2, v46
	v_mul_u32_u24_e32 v11, 0x84, v1
	v_lshl_add_u64 v[8:9], v[26:27], 0, s[2:3]
	v_lshlrev_b32_e32 v1, 2, v47
	s_mov_b64 s[2:3], 0x1c80000
	v_add_u32_e32 v4, v10, v28
	v_add3_u32 v48, v10, v11, v1
	v_lshl_add_u64 v[10:11], v[26:27], 0, s[2:3]
	s_mov_b64 s[2:3], 0x1480000
	v_lshl_add_u64 v[12:13], v[26:27], 0, s[2:3]
	s_mov_b64 s[2:3], 0x2480000
	v_lshl_add_u64 v[14:15], v[26:27], 0, s[2:3]
	s_mov_b64 s[2:3], 0x2780000
	v_lshl_add_u64 v[16:17], v[26:27], 0, s[2:3]
	s_mov_b64 s[2:3], 0x2680000
	v_lshl_add_u64 v[18:19], v[26:27], 0, s[2:3]
	s_mov_b64 s[2:3], 0x2950000
	v_lshl_add_u64 v[20:21], v[26:27], 0, s[2:3]
	s_mov_b64 s[2:3], 0x2910000
	v_lshl_add_u64 v[22:23], v[26:27], 0, s[2:3]
	s_mov_b64 s[2:3], 0x2880000
	v_lshl_add_u64 v[24:25], v[26:27], 0, s[2:3]
	s_mov_b64 s[2:3], 0xb00000
	v_mul_u32_u24_e32 v6, 0x84, v2
	v_lshl_add_u64 v[26:27], v[26:27], 0, s[2:3]
	s_add_u32 s2, s92, 0x800000
	v_or_b32_e32 v3, v3, v6
	s_movk_i32 s25, 0x84
	v_or_b32_e32 v49, 8, v47
	v_or_b32_e32 v50, 16, v47
	v_or_b32_e32 v51, 24, v47
	s_addc_u32 s3, s93, 0
	v_or_b32_e32 v52, 64, v46
	v_mov_b32_e32 v1, v2
	v_add3_u32 v53, v3, v28, 0
	v_or_b32_e32 v54, 14, v2
	v_or_b32_e32 v55, 12, v2
	v_or_b32_e32 v56, 10, v2
	v_or_b32_e32 v57, 8, v2
	v_or_b32_e32 v58, 6, v2
	v_or_b32_e32 v59, 4, v2
	v_or_b32_e32 v60, 2, v2
	s_mov_b64 s[4:5], 0
	s_movk_i32 s36, 0x97f
	s_movk_i32 s37, 0xc00
	s_movk_i32 s38, 0x4ac0
	v_mov_b32_e32 v61, 0x2c0
	v_mov_b32_e32 v62, 0x3c0
	v_mov_b32_e32 v63, 0xffffff80
	v_mov_b32_e32 v64, 5
	v_readlane_b32 s10, v253, 4
	v_readlane_b32 s11, v253, 5
	s_branch .LBB0_79

.LBB0_78:
	s_or_b64 exec, exec, s[8:9]
	v_add_u32_e32 v5, s24, v5
	s_movk_i32 s8, 0x98f
	v_cmp_lt_i32_e32 vcc, s8, v5
	s_or_b64 s[4:5], vcc, s[4:5]
	s_andn2_b64 exec, exec, s[4:5]
	s_cbranch_execz .LBB0_170

.LBB0_671:
	s_waitcnt vmcnt(0)
	s_barrier
	s_cmp_lt_u32 s74, 32
	s_cbranch_scc1 .Lmy_lt_skip
	v_readlane_b32 s2, v253, 0
	v_readlane_b32 s3, v253, 1
	s_sub_u32 s2, s2, 0xf0
	s_subb_u32 s3, s3, 0
	s_load_dwordx4 s[88:91], s[2:3], 0xc0
	s_load_dwordx2 s[92:93], s[2:3], 0xd0
	s_movk_i32 s24, 0x700
	v_mov_b32_e32 v1, v202
	v_ashrrev_i32_e32 v2, 6, v1
	s_sub_i32 s0, s74, 32
	v_lshl_add_u32 v3, s0, 3, v2
	s_waitcnt lgkmcnt(0)
	s_movk_i32 s0, 0x700
	v_cmp_gt_i32_e32 vcc, s0, v3
	s_and_saveexec_b64 s[0:1], vcc
	s_cbranch_execz .Lmy_lt_170
	s_movk_i32 s2, 0x2100
	v_add_u32_e32 v5, 0x990, v3
	v_mul_lo_u32 v3, v2, s2
	v_and_b32_e32 v46, 31, v1
	v_bfe_u32 v2, v1, 5, 1
	v_bfe_u32 v47, v1, 3, 3
	v_lshlrev_b32_e32 v1, 3, v1
	v_and_b32_e32 v1, 56, v1
	v_readlane_b32 s8, v253, 2
	v_lshlrev_b32_e32 v6, 1, v1
	v_mov_b32_e32 v7, 0
	v_readlane_b32 s9, v253, 3
	s_mov_b64 s[2:3], 0x2080000
	v_add_u32_e32 v10, 0, v3
	v_lshl_add_u64 v[26:27], s[8:9], 0, v[6:7]
	v_lshlrev_b32_e32 v28, 2, v46
	v_mul_u32_u24_e32 v11, 0x84, v1
	v_lshl_add_u64 v[8:9], v[26:27], 0, s[2:3]
	v_lshlrev_b32_e32 v1, 2, v47
	s_mov_b64 s[2:3], 0x1c80000
	v_add_u32_e32 v4, v10, v28
	v_add3_u32 v48, v10, v11, v1
	v_lshl_add_u64 v[10:11], v[26:27], 0, s[2:3]
	s_mov_b64 s[2:3], 0x1480000
	v_lshl_add_u64 v[12:13], v[26:27], 0, s[2:3]
	s_mov_b64 s[2:3], 0x2480000
	v_lshl_add_u64 v[14:15], v[26:27], 0, s[2:3]
	s_mov_b64 s[2:3], 0x2780000
	v_lshl_add_u64 v[16:17], v[26:27], 0, s[2:3]
	s_mov_b64 s[2:3], 0x2680000
	v_lshl_add_u64 v[18:19], v[26:27], 0, s[2:3]
	s_mov_b64 s[2:3], 0x2950000
	v_lshl_add_u64 v[20:21], v[26:27], 0, s[2:3]
	s_mov_b64 s[2:3], 0x2910000
	v_lshl_add_u64 v[22:23], v[26:27], 0, s[2:3]
	s_mov_b64 s[2:3], 0x2880000
	v_lshl_add_u64 v[24:25], v[26:27], 0, s[2:3]
	s_mov_b64 s[2:3], 0xb00000
	v_mul_u32_u24_e32 v6, 0x84, v2
	v_lshl_add_u64 v[26:27], v[26:27], 0, s[2:3]
	s_add_u32 s2, s92, 0x800000
	v_or_b32_e32 v3, v3, v6
	s_movk_i32 s25, 0x84
	v_or_b32_e32 v49, 8, v47
	v_or_b32_e32 v50, 16, v47
	v_or_b32_e32 v51, 24, v47
	s_addc_u32 s3, s93, 0
	v_or_b32_e32 v52, 64, v46
	v_mov_b32_e32 v1, v2
	v_add3_u32 v53, v3, v28, 0
	v_or_b32_e32 v54, 14, v2
	v_or_b32_e32 v55, 12, v2
	v_or_b32_e32 v56, 10, v2
	v_or_b32_e32 v57, 8, v2
	v_or_b32_e32 v58, 6, v2
	v_or_b32_e32 v59, 4, v2
	v_or_b32_e32 v60, 2, v2
	s_mov_b64 s[4:5], 0
	s_movk_i32 s36, 0x97f
	s_movk_i32 s37, 0xc00
	s_movk_i32 s38, 0x4ac0
	v_mov_b32_e32 v61, 0x2c0
	v_mov_b32_e32 v62, 0x3c0
	v_mov_b32_e32 v63, 0xffffff80
	v_mov_b32_e32 v64, 5
	v_readlane_b32 s10, v253, 4
	v_readlane_b32 s11, v253, 5
	s_branch .Lmy_lt_79

.Lmy_lt_79:


	v_cmp_lt_i32_e32 vcc, s36, v5
	s_and_saveexec_b64 s[8:9], vcc
	s_xor_b64 s[8:9], exec, s[8:9]
	s_cbranch_execz .Lmy_lt_131

	s_movk_i32 s10, 0xa0f
	v_cmp_lt_u32_e32 vcc, s10, v5
	s_and_saveexec_b64 s[10:11], vcc
	s_xor_b64 s[10:11], exec, s[10:11]
	s_cbranch_execz .Lmy_lt_126

	s_movk_i32 s12, 0xa4f
	v_cmp_lt_u32_e32 vcc, s12, v5
	s_and_saveexec_b64 s[12:13], vcc
	s_xor_b64 s[12:13], exec, s[12:13]
	s_cbranch_execz .Lmy_lt_121

	s_movk_i32 s14, 0xa8f
	v_cmp_lt_u32_e32 vcc, s14, v5
	s_and_saveexec_b64 s[14:15], vcc
	s_xor_b64 s[14:15], exec, s[14:15]
	s_cbranch_execz .Lmy_lt_116

	s_movk_i32 s16, 0xb8f
	v_cmp_lt_u32_e32 vcc, s16, v5
	s_and_saveexec_b64 s[16:17], vcc
	s_xor_b64 s[16:17], exec, s[16:17]
	s_cbranch_execz .Lmy_lt_111

	s_movk_i32 s18, 0xc8f
	v_cmp_lt_u32_e32 vcc, s18, v5
	s_and_saveexec_b64 s[18:19], vcc
	s_xor_b64 s[18:19], exec, s[18:19]
	s_cbranch_execz .Lmy_lt_106

	s_movk_i32 s20, 0xe8f
	v_cmp_lt_u32_e32 vcc, s20, v5
	s_and_saveexec_b64 s[20:21], vcc
	s_xor_b64 s[20:21], exec, s[20:21]
	s_cbranch_execz .Lmy_lt_101

	s_movk_i32 s22, 0x168f
	v_cmp_lt_u32_e32 vcc, s22, v5
	s_and_saveexec_b64 s[22:23], vcc
	s_xor_b64 s[22:23], exec, s[22:23]
	s_cbranch_execz .Lmy_lt_96

	s_movk_i32 s26, 0x1a8f
	v_cmp_lt_u32_e32 vcc, s26, v5
	s_and_saveexec_b64 s[26:27], vcc
	s_xor_b64 s[26:27], exec, s[26:27]
	s_cbranch_execz .Lmy_lt_91

	v_add_u32_e32 v3, 0xffffe570, v5
	v_lshlrev_b32_e32 v6, 1, v3
	v_lshlrev_b32_e32 v3, 5, v3
	v_and_b32_e32 v31, 0x3e0, v3
	v_or_b32_e32 v3, v31, v46
	v_and_b32_e32 v32, 0x1ffc0, v6
	v_lshlrev_b32_e32 v6, 2, v3
	s_mov_b32 s39, 1
	v_lshl_add_u64 v[28:29], s[2:3], 0, v[6:7]
	v_or_b32_e32 v3, v1, v32
	v_or_b32_e32 v30, v2, v32
	s_mov_b32 s40, 0
	s_mov_b32 s41, 32
.Lmy_lt_89:

	s_lshl_b32 s43, s40, 1
	s_lshl_b32 s42, s39, 1
	v_or_b32_e32 v6, s43, v30
	s_add_i32 s45, s43, 4
	s_add_i32 s44, s42, 4
	s_add_i32 s46, s42, 8
	s_add_i32 s47, s43, 8
	v_lshlrev_b64 v[70:71], 12, v[6:7]
	v_or_b32_e32 v6, s45, v30
	v_mov_b32_e32 v35, v7
	v_mov_b32_e32 v37, v7
	v_mov_b32_e32 v39, v7
	v_or_b32_e32 v34, s42, v3
	s_add_i32 s48, s42, 12
	s_add_i32 s49, s43, 12
	s_add_i32 s50, s42, 16
	s_add_i32 s52, s42, 20
	s_add_i32 s54, s42, 24
	s_add_i32 s56, s42, 28
	v_or_b32_e32 v36, s44, v3
	v_or_b32_e32 v38, s46, v3
	v_lshlrev_b64 v[72:73], 12, v[6:7]
	v_or_b32_e32 v6, s47, v30
	v_mov_b32_e32 v41, v7
	v_mov_b32_e32 v43, v7
	v_mov_b32_e32 v45, v7
	v_mov_b32_e32 v67, v7
	v_mov_b32_e32 v69, v7
	s_add_i32 s51, s43, 16
	v_lshlrev_b64 v[34:35], 12, v[34:35]
	v_or_b32_e32 v40, s48, v3
	v_or_b32_e32 v42, s50, v3
	v_or_b32_e32 v44, s52, v3
	v_or_b32_e32 v66, s54, v3
	v_or_b32_e32 v68, s56, v3
	v_lshl_add_u64 v[70:71], v[28:29], 0, v[70:71]
	v_lshlrev_b64 v[36:37], 12, v[36:37]
	v_lshlrev_b64 v[38:39], 12, v[38:39]
	v_lshlrev_b64 v[74:75], 12, v[6:7]
	v_or_b32_e32 v6, s49, v30
	s_add_i32 s53, s43, 20
	v_lshl_add_u64 v[34:35], v[28:29], 0, v[34:35]
	v_lshlrev_b64 v[40:41], 12, v[40:41]
	v_lshlrev_b64 v[42:43], 12, v[42:43]
	v_lshlrev_b64 v[44:45], 12, v[44:45]
	v_lshlrev_b64 v[66:67], 12, v[66:67]
	v_lshlrev_b64 v[68:69], 12, v[68:69]
	v_lshl_add_u64 v[72:73], v[28:29], 0, v[72:73]
	v_lshl_add_u64 v[36:37], v[28:29], 0, v[36:37]
	v_lshl_add_u64 v[38:39], v[28:29], 0, v[38:39]
	global_load_dword v33, v[70:71], off
	global_load_dword v65, v[34:35], off
	v_lshlrev_b64 v[70:71], 12, v[6:7]
	v_or_b32_e32 v6, s51, v30
	s_add_i32 s55, s43, 24
	v_lshl_add_u64 v[40:41], v[28:29], 0, v[40:41]
	v_lshl_add_u64 v[42:43], v[28:29], 0, v[42:43]
	v_lshl_add_u64 v[44:45], v[28:29], 0, v[44:45]
	v_lshl_add_u64 v[66:67], v[28:29], 0, v[66:67]
	v_lshl_add_u64 v[68:69], v[28:29], 0, v[68:69]
	global_load_dword v86, v[72:73], off
	global_load_dword v87, v[36:37], off
	global_load_dword v88, v[38:39], off
	global_load_dword v89, v[40:41], off
	global_load_dword v90, v[42:43], off
	global_load_dword v91, v[44:45], off
	global_load_dword v92, v[66:67], off
	global_load_dword v93, v[68:69], off
	v_lshl_add_u64 v[36:37], v[28:29], 0, v[70:71]
	v_lshlrev_b64 v[38:39], 12, v[6:7]
	v_or_b32_e32 v6, s53, v30
	s_add_i32 s57, s43, 28
	v_lshl_add_u64 v[34:35], v[28:29], 0, v[74:75]
	global_load_dword v94, v[36:37], off
	global_load_dword v95, v[34:35], off
	v_lshlrev_b64 v[36:37], 12, v[6:7]
	v_or_b32_e32 v6, s55, v30
	v_lshl_add_u64 v[34:35], v[28:29], 0, v[38:39]
	v_lshlrev_b64 v[38:39], 12, v[6:7]
	v_or_b32_e32 v6, s57, v30
	v_lshlrev_b64 v[40:41], 12, v[6:7]
	v_lshl_add_u64 v[40:41], v[28:29], 0, v[40:41]
	v_lshl_add_u64 v[36:37], v[28:29], 0, v[36:37]
	v_lshl_add_u64 v[38:39], v[28:29], 0, v[38:39]
	global_load_dword v6, v[40:41], off
	global_load_dword v96, v[38:39], off
	global_load_dword v97, v[36:37], off
	global_load_dword v98, v[34:35], off
	v_or_b32_e32 v36, s42, v1
	v_or_b32_e32 v34, s43, v2
	s_add_i32 s40, s40, 16
	s_add_i32 s39, s39, 16
	s_add_i32 s41, s41, -16
	v_mad_u64_u32 v[34:35], s[42:43], v34, s25, v[4:5]
	v_mad_u64_u32 v[36:37], s[42:43], v36, s25, v[4:5]
	v_or_b32_e32 v35, s44, v1
	v_or_b32_e32 v37, s45, v2
	v_or_b32_e32 v44, s46, v1
	v_or_b32_e32 v42, s47, v2
	v_or_b32_e32 v68, s48, v1
	v_or_b32_e32 v66, s49, v2
	v_or_b32_e32 v72, s50, v1
	v_or_b32_e32 v70, s51, v2
	v_or_b32_e32 v76, s52, v1
	v_or_b32_e32 v74, s53, v2
	v_or_b32_e32 v80, s54, v1
	v_or_b32_e32 v78, s55, v2
	v_or_b32_e32 v84, s56, v1
	v_or_b32_e32 v82, s57, v2
	s_cmp_lg_u32 s41, 0
	v_mad_u64_u32 v[38:39], s[42:43], v37, s25, v[4:5]
	v_mad_u64_u32 v[40:41], s[42:43], v35, s25, v[4:5]
	v_mad_u64_u32 v[42:43], s[42:43], v42, s25, v[4:5]
	v_mad_u64_u32 v[44:45], s[42:43], v44, s25, v[4:5]
	v_mad_u64_u32 v[66:67], s[42:43], v66, s25, v[4:5]
	v_mad_u64_u32 v[68:69], s[42:43], v68, s25, v[4:5]
	v_mad_u64_u32 v[70:71], s[42:43], v70, s25, v[4:5]
	v_mad_u64_u32 v[72:73], s[42:43], v72, s25, v[4:5]
	v_mad_u64_u32 v[74:75], s[42:43], v74, s25, v[4:5]
	v_mad_u64_u32 v[76:77], s[42:43], v76, s25, v[4:5]
	v_mad_u64_u32 v[78:79], s[42:43], v78, s25, v[4:5]
	v_mad_u64_u32 v[80:81], s[42:43], v80, s25, v[4:5]
	v_mad_u64_u32 v[82:83], s[42:43], v82, s25, v[4:5]
	v_mad_u64_u32 v[84:85], s[42:43], v84, s25, v[4:5]
	s_waitcnt vmcnt(15)
	ds_write_b32 v34, v33
	s_waitcnt vmcnt(14)
	ds_write_b32 v36, v65
	s_waitcnt vmcnt(13)
	ds_write_b32 v38, v86
	s_waitcnt vmcnt(12)
	ds_write_b32 v40, v87
	s_waitcnt vmcnt(4)
	ds_write_b32 v42, v95
	ds_write_b32 v44, v88
	ds_write_b32 v66, v94
	ds_write_b32 v68, v89
	s_waitcnt vmcnt(0)
	ds_write_b32 v70, v98
	ds_write_b32 v72, v90
	ds_write_b32 v74, v97
	ds_write_b32 v76, v91
	ds_write_b32 v78, v96
	ds_write_b32 v80, v92
	ds_write_b32 v82, v6
	ds_write_b32 v84, v93
	s_cbranch_scc1 .Lmy_lt_89

	s_waitcnt lgkmcnt(0)
	ds_read2_b32 v[28:29], v48 offset1:33
	s_waitcnt lgkmcnt(0)
	v_cvt_pk_bf16_f32 v34, v28, v29
	ds_read2_b32 v[28:29], v48 offset0:66 offset1:99
	s_waitcnt lgkmcnt(0)
	v_cvt_pk_bf16_f32 v35, v28, v29
	ds_read2_b32 v[28:29], v48 offset0:132 offset1:165
	v_lshlrev_b32_e32 v6, 1, v32
	v_or_b32_e32 v3, v31, v47
	s_waitcnt lgkmcnt(0)
	v_cvt_pk_bf16_f32 v36, v28, v29
	ds_read2_b32 v[28:29], v48 offset0:198 offset1:231
	v_lshl_add_u64 v[38:39], v[8:9], 0, v[6:7]
	v_lshlrev_b32_e32 v6, 12, v3
	s_waitcnt lgkmcnt(0)
	v_cvt_pk_bf16_f32 v37, v28, v29
	ds_read2_b32 v[28:29], v48 offset0:8 offset1:41
	v_lshl_add_u64 v[32:33], v[38:39], 0, v[6:7]
	global_store_dwordx4 v[32:33], v[34:37], off
	s_waitcnt lgkmcnt(0)
	v_cvt_pk_bf16_f32 v32, v28, v29
	ds_read2_b32 v[28:29], v48 offset0:74 offset1:107
	s_waitcnt lgkmcnt(0)
	v_cvt_pk_bf16_f32 v33, v28, v29
	ds_read2_b32 v[28:29], v48 offset0:140 offset1:173
	v_or_b32_e32 v3, v31, v49
	s_waitcnt lgkmcnt(0)
	v_cvt_pk_bf16_f32 v34, v28, v29
	ds_read2_b32 v[28:29], v48 offset0:206 offset1:239
	v_lshlrev_b32_e32 v6, 12, v3
	s_waitcnt lgkmcnt(0)
	v_cvt_pk_bf16_f32 v35, v28, v29
	ds_read2_b32 v[28:29], v48 offset0:16 offset1:49
	v_lshl_add_u64 v[36:37], v[38:39], 0, v[6:7]
	global_store_dwordx4 v[36:37], v[32:35], off
	v_or_b32_e32 v3, v31, v50
	v_lshlrev_b32_e32 v6, 12, v3
	s_waitcnt lgkmcnt(0)
	v_cvt_pk_bf16_f32 v32, v28, v29
	ds_read2_b32 v[28:29], v48 offset0:82 offset1:115
	s_waitcnt lgkmcnt(0)
	v_cvt_pk_bf16_f32 v33, v28, v29
	ds_read2_b32 v[28:29], v48 offset0:148 offset1:181
	s_waitcnt lgkmcnt(0)
	v_cvt_pk_bf16_f32 v34, v28, v29
	ds_read2_b32 v[28:29], v48 offset0:214 offset1:247
	s_waitcnt lgkmcnt(0)
	v_cvt_pk_bf16_f32 v35, v28, v29
	ds_read2_b32 v[28:29], v48 offset0:24 offset1:57
	v_lshl_add_u64 v[36:37], v[38:39], 0, v[6:7]
	global_store_dwordx4 v[36:37], v[32:35], off
	s_waitcnt lgkmcnt(0)
	v_cvt_pk_bf16_f32 v28, v28, v29
	ds_read2_b32 v[32:33], v48 offset0:90 offset1:123
	s_waitcnt lgkmcnt(0)
	v_cvt_pk_bf16_f32 v29, v32, v33
	ds_read2_b32 v[32:33], v48 offset0:156 offset1:189
	v_or_b32_e32 v3, v31, v51
	s_waitcnt lgkmcnt(0)
	v_cvt_pk_bf16_f32 v30, v32, v33
	ds_read2_b32 v[32:33], v48 offset0:222 offset1:255
	v_lshlrev_b32_e32 v6, 12, v3
	s_waitcnt lgkmcnt(0)
	v_cvt_pk_bf16_f32 v31, v32, v33
	v_lshl_add_u64 v[32:33], v[38:39], 0, v[6:7]
	global_store_dwordx4 v[32:33], v[28:31], off
	s_waitcnt lgkmcnt(0)
.Lmy_lt_91:
	s_andn2_saveexec_b64 s[26:27], s[26:27]
	s_cbranch_execz .Lmy_lt_95

	v_add_u32_e32 v3, 0xffffe970, v5
	v_lshlrev_b32_e32 v6, 1, v3
	v_lshlrev_b32_e32 v3, 5, v3
	v_and_b32_e32 v31, 0x3e0, v3
	v_or_b32_e32 v3, v31, v46
	v_and_b32_e32 v32, 0x1ffc0, v6
	v_lshlrev_b32_e32 v6, 2, v3
	s_mov_b32 s39, 1
	v_lshl_add_u64 v[28:29], s[92:93], 0, v[6:7]
	v_or_b32_e32 v3, v1, v32
	v_or_b32_e32 v30, v2, v32
	s_mov_b32 s40, 0
	s_mov_b32 s41, 32
.Lmy_lt_93:

	s_lshl_b32 s43, s40, 1
	s_lshl_b32 s42, s39, 1
	v_or_b32_e32 v6, s43, v30
	s_add_i32 s45, s43, 4
	s_add_i32 s44, s42, 4
	s_add_i32 s46, s42, 8
	s_add_i32 s47, s43, 8
	v_lshlrev_b64 v[70:71], 12, v[6:7]
	v_or_b32_e32 v6, s45, v30
	v_mov_b32_e32 v35, v7
	v_mov_b32_e32 v37, v7
	v_mov_b32_e32 v39, v7
	v_or_b32_e32 v34, s42, v3
	s_add_i32 s48, s42, 12
	s_add_i32 s49, s43, 12
	s_add_i32 s50, s42, 16
	s_add_i32 s52, s42, 20
	s_add_i32 s54, s42, 24
	s_add_i32 s56, s42, 28
	v_or_b32_e32 v36, s44, v3
	v_or_b32_e32 v38, s46, v3
	v_lshlrev_b64 v[72:73], 12, v[6:7]
	v_or_b32_e32 v6, s47, v30
	v_mov_b32_e32 v41, v7
	v_mov_b32_e32 v43, v7
	v_mov_b32_e32 v45, v7
	v_mov_b32_e32 v67, v7
	v_mov_b32_e32 v69, v7
	s_add_i32 s51, s43, 16
	v_lshlrev_b64 v[34:35], 12, v[34:35]
	v_or_b32_e32 v40, s48, v3
	v_or_b32_e32 v42, s50, v3
	v_or_b32_e32 v44, s52, v3
	v_or_b32_e32 v66, s54, v3
	v_or_b32_e32 v68, s56, v3
	v_lshl_add_u64 v[70:71], v[28:29], 0, v[70:71]
	v_lshlrev_b64 v[36:37], 12, v[36:37]
	v_lshlrev_b64 v[38:39], 12, v[38:39]
	v_lshlrev_b64 v[74:75], 12, v[6:7]
	v_or_b32_e32 v6, s49, v30
	s_add_i32 s53, s43, 20
	v_lshl_add_u64 v[34:35], v[28:29], 0, v[34:35]
	v_lshlrev_b64 v[40:41], 12, v[40:41]
	v_lshlrev_b64 v[42:43], 12, v[42:43]
	v_lshlrev_b64 v[44:45], 12, v[44:45]
	v_lshlrev_b64 v[66:67], 12, v[66:67]
	v_lshlrev_b64 v[68:69], 12, v[68:69]
	v_lshl_add_u64 v[72:73], v[28:29], 0, v[72:73]
	v_lshl_add_u64 v[36:37], v[28:29], 0, v[36:37]
	v_lshl_add_u64 v[38:39], v[28:29], 0, v[38:39]
	global_load_dword v33, v[70:71], off
	global_load_dword v65, v[34:35], off
	v_lshlrev_b64 v[70:71], 12, v[6:7]
	v_or_b32_e32 v6, s51, v30
	s_add_i32 s55, s43, 24
	v_lshl_add_u64 v[40:41], v[28:29], 0, v[40:41]
	v_lshl_add_u64 v[42:43], v[28:29], 0, v[42:43]
	v_lshl_add_u64 v[44:45], v[28:29], 0, v[44:45]
	v_lshl_add_u64 v[66:67], v[28:29], 0, v[66:67]
	v_lshl_add_u64 v[68:69], v[28:29], 0, v[68:69]
	global_load_dword v86, v[72:73], off
	global_load_dword v87, v[36:37], off
	global_load_dword v88, v[38:39], off
	global_load_dword v89, v[40:41], off
	global_load_dword v90, v[42:43], off
	global_load_dword v91, v[44:45], off
	global_load_dword v92, v[66:67], off
	global_load_dword v93, v[68:69], off
	v_lshl_add_u64 v[36:37], v[28:29], 0, v[70:71]
	v_lshlrev_b64 v[38:39], 12, v[6:7]
	v_or_b32_e32 v6, s53, v30
	s_add_i32 s57, s43, 28
	v_lshl_add_u64 v[34:35], v[28:29], 0, v[74:75]
	global_load_dword v94, v[36:37], off
	global_load_dword v95, v[34:35], off
	v_lshlrev_b64 v[36:37], 12, v[6:7]
	v_or_b32_e32 v6, s55, v30
	v_lshl_add_u64 v[34:35], v[28:29], 0, v[38:39]
	v_lshlrev_b64 v[38:39], 12, v[6:7]
	v_or_b32_e32 v6, s57, v30
	v_lshlrev_b64 v[40:41], 12, v[6:7]
	v_lshl_add_u64 v[40:41], v[28:29], 0, v[40:41]
	v_lshl_add_u64 v[36:37], v[28:29], 0, v[36:37]
	v_lshl_add_u64 v[38:39], v[28:29], 0, v[38:39]
	global_load_dword v6, v[40:41], off
	global_load_dword v96, v[38:39], off
	global_load_dword v97, v[36:37], off
	global_load_dword v98, v[34:35], off
	v_or_b32_e32 v36, s42, v1
	v_or_b32_e32 v34, s43, v2
	s_add_i32 s40, s40, 16
	s_add_i32 s39, s39, 16
	s_add_i32 s41, s41, -16
	v_mad_u64_u32 v[34:35], s[42:43], v34, s25, v[4:5]
	v_mad_u64_u32 v[36:37], s[42:43], v36, s25, v[4:5]
	v_or_b32_e32 v35, s44, v1
	v_or_b32_e32 v37, s45, v2
	v_or_b32_e32 v44, s46, v1
	v_or_b32_e32 v42, s47, v2
	v_or_b32_e32 v68, s48, v1
	v_or_b32_e32 v66, s49, v2
	v_or_b32_e32 v72, s50, v1
	v_or_b32_e32 v70, s51, v2
	v_or_b32_e32 v76, s52, v1
	v_or_b32_e32 v74, s53, v2
	v_or_b32_e32 v80, s54, v1
	v_or_b32_e32 v78, s55, v2
	v_or_b32_e32 v84, s56, v1
	v_or_b32_e32 v82, s57, v2
	s_cmp_lg_u32 s41, 0
	v_mad_u64_u32 v[38:39], s[42:43], v37, s25, v[4:5]
	v_mad_u64_u32 v[40:41], s[42:43], v35, s25, v[4:5]
	v_mad_u64_u32 v[42:43], s[42:43], v42, s25, v[4:5]
	v_mad_u64_u32 v[44:45], s[42:43], v44, s25, v[4:5]
	v_mad_u64_u32 v[66:67], s[42:43], v66, s25, v[4:5]
	v_mad_u64_u32 v[68:69], s[42:43], v68, s25, v[4:5]
	v_mad_u64_u32 v[70:71], s[42:43], v70, s25, v[4:5]
	v_mad_u64_u32 v[72:73], s[42:43], v72, s25, v[4:5]
	v_mad_u64_u32 v[74:75], s[42:43], v74, s25, v[4:5]
	v_mad_u64_u32 v[76:77], s[42:43], v76, s25, v[4:5]
	v_mad_u64_u32 v[78:79], s[42:43], v78, s25, v[4:5]
	v_mad_u64_u32 v[80:81], s[42:43], v80, s25, v[4:5]
	v_mad_u64_u32 v[82:83], s[42:43], v82, s25, v[4:5]
	v_mad_u64_u32 v[84:85], s[42:43], v84, s25, v[4:5]
	s_waitcnt vmcnt(15)
	ds_write_b32 v34, v33
	s_waitcnt vmcnt(14)
	ds_write_b32 v36, v65
	s_waitcnt vmcnt(13)
	ds_write_b32 v38, v86
	s_waitcnt vmcnt(12)
	ds_write_b32 v40, v87
	s_waitcnt vmcnt(4)
	ds_write_b32 v42, v95
	ds_write_b32 v44, v88
	ds_write_b32 v66, v94
	ds_write_b32 v68, v89
	s_waitcnt vmcnt(0)
	ds_write_b32 v70, v98
	ds_write_b32 v72, v90
	ds_write_b32 v74, v97
	ds_write_b32 v76, v91
	ds_write_b32 v78, v96
	ds_write_b32 v80, v92
	ds_write_b32 v82, v6
	ds_write_b32 v84, v93
	s_cbranch_scc1 .Lmy_lt_93

	s_waitcnt lgkmcnt(0)
	ds_read2_b32 v[28:29], v48 offset1:33
	s_waitcnt lgkmcnt(0)
	v_cvt_pk_bf16_f32 v34, v28, v29
	ds_read2_b32 v[28:29], v48 offset0:66 offset1:99
	s_waitcnt lgkmcnt(0)
	v_cvt_pk_bf16_f32 v35, v28, v29
	ds_read2_b32 v[28:29], v48 offset0:132 offset1:165
	v_lshlrev_b32_e32 v6, 1, v32
	v_or_b32_e32 v3, v31, v47
	s_waitcnt lgkmcnt(0)
	v_cvt_pk_bf16_f32 v36, v28, v29
	ds_read2_b32 v[28:29], v48 offset0:198 offset1:231
	v_lshl_add_u64 v[38:39], v[10:11], 0, v[6:7]
	v_lshlrev_b32_e32 v6, 12, v3
	s_waitcnt lgkmcnt(0)
	v_cvt_pk_bf16_f32 v37, v28, v29
	ds_read2_b32 v[28:29], v48 offset0:8 offset1:41
	v_lshl_add_u64 v[32:33], v[38:39], 0, v[6:7]
	global_store_dwordx4 v[32:33], v[34:37], off
	s_waitcnt lgkmcnt(0)
	v_cvt_pk_bf16_f32 v32, v28, v29
	ds_read2_b32 v[28:29], v48 offset0:74 offset1:107
	s_waitcnt lgkmcnt(0)
	v_cvt_pk_bf16_f32 v33, v28, v29
	ds_read2_b32 v[28:29], v48 offset0:140 offset1:173
	v_or_b32_e32 v3, v31, v49
	s_waitcnt lgkmcnt(0)
	v_cvt_pk_bf16_f32 v34, v28, v29
	ds_read2_b32 v[28:29], v48 offset0:206 offset1:239
	v_lshlrev_b32_e32 v6, 12, v3
	s_waitcnt lgkmcnt(0)
	v_cvt_pk_bf16_f32 v35, v28, v29
	ds_read2_b32 v[28:29], v48 offset0:16 offset1:49
	v_lshl_add_u64 v[36:37], v[38:39], 0, v[6:7]
	global_store_dwordx4 v[36:37], v[32:35], off
	v_or_b32_e32 v3, v31, v50
	v_lshlrev_b32_e32 v6, 12, v3
	s_waitcnt lgkmcnt(0)
	v_cvt_pk_bf16_f32 v32, v28, v29
	ds_read2_b32 v[28:29], v48 offset0:82 offset1:115
	s_waitcnt lgkmcnt(0)
	v_cvt_pk_bf16_f32 v33, v28, v29
	ds_read2_b32 v[28:29], v48 offset0:148 offset1:181
	s_waitcnt lgkmcnt(0)
	v_cvt_pk_bf16_f32 v34, v28, v29
	ds_read2_b32 v[28:29], v48 offset0:214 offset1:247
	s_waitcnt lgkmcnt(0)
	v_cvt_pk_bf16_f32 v35, v28, v29
	ds_read2_b32 v[28:29], v48 offset0:24 offset1:57
	v_lshl_add_u64 v[36:37], v[38:39], 0, v[6:7]
	global_store_dwordx4 v[36:37], v[32:35], off
	s_waitcnt lgkmcnt(0)
	v_cvt_pk_bf16_f32 v28, v28, v29
	ds_read2_b32 v[32:33], v48 offset0:90 offset1:123
	s_waitcnt lgkmcnt(0)
	v_cvt_pk_bf16_f32 v29, v32, v33
	ds_read2_b32 v[32:33], v48 offset0:156 offset1:189
	v_or_b32_e32 v3, v31, v51
	s_waitcnt lgkmcnt(0)
	v_cvt_pk_bf16_f32 v30, v32, v33
	ds_read2_b32 v[32:33], v48 offset0:222 offset1:255
	v_lshlrev_b32_e32 v6, 12, v3
	s_waitcnt lgkmcnt(0)
	v_cvt_pk_bf16_f32 v31, v32, v33
	v_lshl_add_u64 v[32:33], v[38:39], 0, v[6:7]
	global_store_dwordx4 v[32:33], v[28:31], off
	s_waitcnt lgkmcnt(0)

.Lmy_lt_96:
	s_andn2_saveexec_b64 s[22:23], s[22:23]
	s_cbranch_execz .Lmy_lt_100

	v_add_u32_e32 v3, 0xfffff170, v5
	v_lshrrev_b32_e32 v6, 1, v3
	v_lshlrev_b32_e32 v3, 5, v3
	v_and_b32_e32 v31, 0xfe0, v3
	v_or_b32_e32 v3, v31, v46
	v_and_b32_e32 v32, 0x7fc0, v6
	v_lshlrev_b32_e32 v6, 2, v3
	s_mov_b32 s26, 1
	v_lshl_add_u64 v[28:29], s[90:91], 0, v[6:7]
	v_or_b32_e32 v3, v1, v32
	v_or_b32_e32 v30, v2, v32
	s_mov_b32 s27, 0
	s_mov_b32 s39, 32
.Lmy_lt_98:

	s_lshl_b32 s41, s27, 1
	s_lshl_b32 s40, s26, 1
	v_or_b32_e32 v6, s41, v30
	s_add_i32 s43, s41, 4
	s_add_i32 s42, s40, 4
	s_add_i32 s44, s40, 8
	s_add_i32 s45, s41, 8
	v_lshlrev_b64 v[70:71], 14, v[6:7]
	v_or_b32_e32 v6, s43, v30
	v_mov_b32_e32 v35, v7
	v_mov_b32_e32 v37, v7
	v_mov_b32_e32 v39, v7
	v_or_b32_e32 v34, s40, v3
	s_add_i32 s46, s40, 12
	s_add_i32 s47, s41, 12
	s_add_i32 s48, s40, 16
	s_add_i32 s50, s40, 20
	s_add_i32 s52, s40, 24
	s_add_i32 s54, s40, 28
	v_or_b32_e32 v36, s42, v3
	v_or_b32_e32 v38, s44, v3
	v_lshlrev_b64 v[72:73], 14, v[6:7]
	v_or_b32_e32 v6, s45, v30
	v_mov_b32_e32 v41, v7
	v_mov_b32_e32 v43, v7
	v_mov_b32_e32 v45, v7
	v_mov_b32_e32 v67, v7
	v_mov_b32_e32 v69, v7
	s_add_i32 s49, s41, 16
	v_lshlrev_b64 v[34:35], 14, v[34:35]
	v_or_b32_e32 v40, s46, v3
	v_or_b32_e32 v42, s48, v3
	v_or_b32_e32 v44, s50, v3
	v_or_b32_e32 v66, s52, v3
	v_or_b32_e32 v68, s54, v3
	v_lshl_add_u64 v[70:71], v[28:29], 0, v[70:71]
	v_lshlrev_b64 v[36:37], 14, v[36:37]
	v_lshlrev_b64 v[38:39], 14, v[38:39]
	v_lshlrev_b64 v[74:75], 14, v[6:7]
	v_or_b32_e32 v6, s47, v30
	s_add_i32 s51, s41, 20
	v_lshl_add_u64 v[34:35], v[28:29], 0, v[34:35]
	v_lshlrev_b64 v[40:41], 14, v[40:41]
	v_lshlrev_b64 v[42:43], 14, v[42:43]
	v_lshlrev_b64 v[44:45], 14, v[44:45]
	v_lshlrev_b64 v[66:67], 14, v[66:67]
	v_lshlrev_b64 v[68:69], 14, v[68:69]
	v_lshl_add_u64 v[72:73], v[28:29], 0, v[72:73]
	v_lshl_add_u64 v[36:37], v[28:29], 0, v[36:37]
	v_lshl_add_u64 v[38:39], v[28:29], 0, v[38:39]
	global_load_dword v33, v[70:71], off
	global_load_dword v65, v[34:35], off
	v_lshlrev_b64 v[70:71], 14, v[6:7]
	v_or_b32_e32 v6, s49, v30
	s_add_i32 s53, s41, 24
	v_lshl_add_u64 v[40:41], v[28:29], 0, v[40:41]
	v_lshl_add_u64 v[42:43], v[28:29], 0, v[42:43]
	v_lshl_add_u64 v[44:45], v[28:29], 0, v[44:45]
	v_lshl_add_u64 v[66:67], v[28:29], 0, v[66:67]
	v_lshl_add_u64 v[68:69], v[28:29], 0, v[68:69]
	global_load_dword v86, v[72:73], off
	global_load_dword v87, v[36:37], off
	global_load_dword v88, v[38:39], off
	global_load_dword v89, v[40:41], off
	global_load_dword v90, v[42:43], off
	global_load_dword v91, v[44:45], off
	global_load_dword v92, v[66:67], off
	global_load_dword v93, v[68:69], off
	v_lshl_add_u64 v[36:37], v[28:29], 0, v[70:71]
	v_lshlrev_b64 v[38:39], 14, v[6:7]
	v_or_b32_e32 v6, s51, v30
	s_add_i32 s55, s41, 28
	v_lshl_add_u64 v[34:35], v[28:29], 0, v[74:75]
	global_load_dword v94, v[36:37], off
	global_load_dword v95, v[34:35], off
	v_lshlrev_b64 v[36:37], 14, v[6:7]
	v_or_b32_e32 v6, s53, v30
	v_lshl_add_u64 v[34:35], v[28:29], 0, v[38:39]
	v_lshlrev_b64 v[38:39], 14, v[6:7]
	v_or_b32_e32 v6, s55, v30
	v_lshlrev_b64 v[40:41], 14, v[6:7]
	v_lshl_add_u64 v[40:41], v[28:29], 0, v[40:41]
	v_lshl_add_u64 v[36:37], v[28:29], 0, v[36:37]
	v_lshl_add_u64 v[38:39], v[28:29], 0, v[38:39]
	global_load_dword v6, v[40:41], off
	global_load_dword v96, v[38:39], off
	global_load_dword v97, v[36:37], off
	global_load_dword v98, v[34:35], off
	v_or_b32_e32 v36, s40, v1
	v_or_b32_e32 v34, s41, v2
	s_add_i32 s27, s27, 16
	s_add_i32 s26, s26, 16
	s_add_i32 s39, s39, -16
	v_mad_u64_u32 v[34:35], s[40:41], v34, s25, v[4:5]
	v_mad_u64_u32 v[36:37], s[40:41], v36, s25, v[4:5]
	v_or_b32_e32 v35, s42, v1
	v_or_b32_e32 v37, s43, v2
	v_or_b32_e32 v44, s44, v1
	v_or_b32_e32 v42, s45, v2
	v_or_b32_e32 v68, s46, v1
	v_or_b32_e32 v66, s47, v2
	v_or_b32_e32 v72, s48, v1
	v_or_b32_e32 v70, s49, v2
	v_or_b32_e32 v76, s50, v1
	v_or_b32_e32 v74, s51, v2
	v_or_b32_e32 v80, s52, v1
	v_or_b32_e32 v78, s53, v2
	v_or_b32_e32 v84, s54, v1
	v_or_b32_e32 v82, s55, v2
	s_cmp_lg_u32 s39, 0
	v_mad_u64_u32 v[38:39], s[40:41], v37, s25, v[4:5]
	v_mad_u64_u32 v[40:41], s[40:41], v35, s25, v[4:5]
	v_mad_u64_u32 v[42:43], s[40:41], v42, s25, v[4:5]
	v_mad_u64_u32 v[44:45], s[40:41], v44, s25, v[4:5]
	v_mad_u64_u32 v[66:67], s[40:41], v66, s25, v[4:5]
	v_mad_u64_u32 v[68:69], s[40:41], v68, s25, v[4:5]
	v_mad_u64_u32 v[70:71], s[40:41], v70, s25, v[4:5]
	v_mad_u64_u32 v[72:73], s[40:41], v72, s25, v[4:5]
	v_mad_u64_u32 v[74:75], s[40:41], v74, s25, v[4:5]
	v_mad_u64_u32 v[76:77], s[40:41], v76, s25, v[4:5]
	v_mad_u64_u32 v[78:79], s[40:41], v78, s25, v[4:5]
	v_mad_u64_u32 v[80:81], s[40:41], v80, s25, v[4:5]
	v_mad_u64_u32 v[82:83], s[40:41], v82, s25, v[4:5]
	v_mad_u64_u32 v[84:85], s[40:41], v84, s25, v[4:5]
	s_waitcnt vmcnt(15)
	ds_write_b32 v34, v33
	s_waitcnt vmcnt(14)
	ds_write_b32 v36, v65
	s_waitcnt vmcnt(13)
	ds_write_b32 v38, v86
	s_waitcnt vmcnt(12)
	ds_write_b32 v40, v87
	s_waitcnt vmcnt(4)
	ds_write_b32 v42, v95
	ds_write_b32 v44, v88
	ds_write_b32 v66, v94
	ds_write_b32 v68, v89
	s_waitcnt vmcnt(0)
	ds_write_b32 v70, v98
	ds_write_b32 v72, v90
	ds_write_b32 v74, v97
	ds_write_b32 v76, v91
	ds_write_b32 v78, v96
	ds_write_b32 v80, v92
	ds_write_b32 v82, v6
	ds_write_b32 v84, v93
	s_cbranch_scc1 .Lmy_lt_98

	s_waitcnt lgkmcnt(0)
	ds_read2_b32 v[28:29], v48 offset1:33
	s_waitcnt lgkmcnt(0)
	v_cvt_pk_bf16_f32 v34, v28, v29
	ds_read2_b32 v[28:29], v48 offset0:66 offset1:99
	s_waitcnt lgkmcnt(0)
	v_cvt_pk_bf16_f32 v35, v28, v29
	ds_read2_b32 v[28:29], v48 offset0:132 offset1:165
	v_lshlrev_b32_e32 v6, 1, v32
	v_or_b32_e32 v3, v31, v47
	s_waitcnt lgkmcnt(0)
	v_cvt_pk_bf16_f32 v36, v28, v29
	ds_read2_b32 v[28:29], v48 offset0:198 offset1:231
	v_lshl_add_u64 v[38:39], v[12:13], 0, v[6:7]
	v_lshlrev_b32_e32 v6, 11, v3
	s_waitcnt lgkmcnt(0)
	v_cvt_pk_bf16_f32 v37, v28, v29
	ds_read2_b32 v[28:29], v48 offset0:8 offset1:41
	v_lshl_add_u64 v[32:33], v[38:39], 0, v[6:7]
	global_store_dwordx4 v[32:33], v[34:37], off
	s_waitcnt lgkmcnt(0)
	v_cvt_pk_bf16_f32 v32, v28, v29
	ds_read2_b32 v[28:29], v48 offset0:74 offset1:107
	s_waitcnt lgkmcnt(0)
	v_cvt_pk_bf16_f32 v33, v28, v29
	ds_read2_b32 v[28:29], v48 offset0:140 offset1:173
	v_or_b32_e32 v3, v31, v49
	s_waitcnt lgkmcnt(0)
	v_cvt_pk_bf16_f32 v34, v28, v29
	ds_read2_b32 v[28:29], v48 offset0:206 offset1:239
	v_lshlrev_b32_e32 v6, 11, v3
	s_waitcnt lgkmcnt(0)
	v_cvt_pk_bf16_f32 v35, v28, v29
	ds_read2_b32 v[28:29], v48 offset0:16 offset1:49
	v_lshl_add_u64 v[36:37], v[38:39], 0, v[6:7]
	global_store_dwordx4 v[36:37], v[32:35], off
	v_or_b32_e32 v3, v31, v50
	v_lshlrev_b32_e32 v6, 11, v3
	s_waitcnt lgkmcnt(0)
	v_cvt_pk_bf16_f32 v32, v28, v29
	ds_read2_b32 v[28:29], v48 offset0:82 offset1:115
	s_waitcnt lgkmcnt(0)
	v_cvt_pk_bf16_f32 v33, v28, v29
	ds_read2_b32 v[28:29], v48 offset0:148 offset1:181
	s_waitcnt lgkmcnt(0)
	v_cvt_pk_bf16_f32 v34, v28, v29
	ds_read2_b32 v[28:29], v48 offset0:214 offset1:247
	s_waitcnt lgkmcnt(0)
	v_cvt_pk_bf16_f32 v35, v28, v29
	ds_read2_b32 v[28:29], v48 offset0:24 offset1:57
	v_lshl_add_u64 v[36:37], v[38:39], 0, v[6:7]
	global_store_dwordx4 v[36:37], v[32:35], off
	s_waitcnt lgkmcnt(0)
	v_cvt_pk_bf16_f32 v28, v28, v29
	ds_read2_b32 v[32:33], v48 offset0:90 offset1:123
	s_waitcnt lgkmcnt(0)
	v_cvt_pk_bf16_f32 v29, v32, v33
	ds_read2_b32 v[32:33], v48 offset0:156 offset1:189
	v_or_b32_e32 v3, v31, v51
	s_waitcnt lgkmcnt(0)
	v_cvt_pk_bf16_f32 v30, v32, v33
	ds_read2_b32 v[32:33], v48 offset0:222 offset1:255
	v_lshlrev_b32_e32 v6, 11, v3
	s_waitcnt lgkmcnt(0)
	v_cvt_pk_bf16_f32 v31, v32, v33
	v_lshl_add_u64 v[32:33], v[38:39], 0, v[6:7]
	global_store_dwordx4 v[32:33], v[28:31], off
	s_waitcnt lgkmcnt(0)

.Lmy_lt_101:
	s_andn2_saveexec_b64 s[20:21], s[20:21]
	s_cbranch_execz .Lmy_lt_105

	v_add_u32_e32 v3, 0xfffff370, v5
	v_lshlrev_b32_e32 v6, 1, v3
	v_lshlrev_b32_e32 v3, 5, v3
	v_and_b32_e32 v31, 0x3e0, v3
	v_or_b32_e32 v3, v31, v46
	v_and_b32_e32 v32, 0x1ffc0, v6
	v_lshlrev_b32_e32 v6, 2, v3
	s_mov_b32 s22, 1
	v_lshl_add_u64 v[28:29], s[88:89], 0, v[6:7]
	v_or_b32_e32 v3, v1, v32
	v_or_b32_e32 v30, v2, v32
	s_mov_b32 s23, 0
	s_mov_b32 s26, 32
.Lmy_lt_103:

	s_lshl_b32 s39, s23, 1
	s_lshl_b32 s27, s22, 1
	v_or_b32_e32 v6, s39, v30
	s_add_i32 s43, s39, 4
	s_add_i32 s42, s27, 4
	s_add_i32 s44, s27, 8
	s_add_i32 s45, s39, 8
	v_lshlrev_b64 v[70:71], 12, v[6:7]
	v_or_b32_e32 v6, s43, v30
	v_mov_b32_e32 v35, v7
	v_mov_b32_e32 v37, v7
	v_mov_b32_e32 v39, v7
	v_or_b32_e32 v34, s27, v3
	s_add_i32 s46, s27, 12
	s_add_i32 s47, s39, 12
	s_add_i32 s48, s27, 16
	s_add_i32 s50, s27, 20
	s_add_i32 s52, s27, 24
	s_add_i32 s54, s27, 28
	v_or_b32_e32 v36, s42, v3
	v_or_b32_e32 v38, s44, v3
	v_lshlrev_b64 v[72:73], 12, v[6:7]
	v_or_b32_e32 v6, s45, v30
	v_mov_b32_e32 v41, v7
	v_mov_b32_e32 v43, v7
	v_mov_b32_e32 v45, v7
	v_mov_b32_e32 v67, v7
	v_mov_b32_e32 v69, v7
	s_add_i32 s49, s39, 16
	v_lshlrev_b64 v[34:35], 12, v[34:35]
	v_or_b32_e32 v40, s46, v3
	v_or_b32_e32 v42, s48, v3
	v_or_b32_e32 v44, s50, v3
	v_or_b32_e32 v66, s52, v3
	v_or_b32_e32 v68, s54, v3
	v_lshl_add_u64 v[70:71], v[28:29], 0, v[70:71]
	v_lshlrev_b64 v[36:37], 12, v[36:37]
	v_lshlrev_b64 v[38:39], 12, v[38:39]
	v_lshlrev_b64 v[74:75], 12, v[6:7]
	v_or_b32_e32 v6, s47, v30
	s_add_i32 s51, s39, 20
	v_lshl_add_u64 v[34:35], v[28:29], 0, v[34:35]
	v_lshlrev_b64 v[40:41], 12, v[40:41]
	v_lshlrev_b64 v[42:43], 12, v[42:43]
	v_lshlrev_b64 v[44:45], 12, v[44:45]
	v_lshlrev_b64 v[66:67], 12, v[66:67]
	v_lshlrev_b64 v[68:69], 12, v[68:69]
	v_lshl_add_u64 v[72:73], v[28:29], 0, v[72:73]
	v_lshl_add_u64 v[36:37], v[28:29], 0, v[36:37]
	v_lshl_add_u64 v[38:39], v[28:29], 0, v[38:39]
	global_load_dword v33, v[70:71], off
	global_load_dword v65, v[34:35], off
	v_lshlrev_b64 v[70:71], 12, v[6:7]
	v_or_b32_e32 v6, s49, v30
	s_add_i32 s53, s39, 24
	v_lshl_add_u64 v[40:41], v[28:29], 0, v[40:41]
	v_lshl_add_u64 v[42:43], v[28:29], 0, v[42:43]
	v_lshl_add_u64 v[44:45], v[28:29], 0, v[44:45]
	v_lshl_add_u64 v[66:67], v[28:29], 0, v[66:67]
	v_lshl_add_u64 v[68:69], v[28:29], 0, v[68:69]
	global_load_dword v86, v[72:73], off
	global_load_dword v87, v[36:37], off
	global_load_dword v88, v[38:39], off
	global_load_dword v89, v[40:41], off
	global_load_dword v90, v[42:43], off
	global_load_dword v91, v[44:45], off
	global_load_dword v92, v[66:67], off
	global_load_dword v93, v[68:69], off
	v_lshl_add_u64 v[36:37], v[28:29], 0, v[70:71]
	v_lshlrev_b64 v[38:39], 12, v[6:7]
	v_or_b32_e32 v6, s51, v30
	s_add_i32 s55, s39, 28
	v_lshl_add_u64 v[34:35], v[28:29], 0, v[74:75]
	global_load_dword v94, v[36:37], off
	global_load_dword v95, v[34:35], off
	v_lshlrev_b64 v[36:37], 12, v[6:7]
	v_or_b32_e32 v6, s53, v30
	v_lshl_add_u64 v[34:35], v[28:29], 0, v[38:39]
	v_lshlrev_b64 v[38:39], 12, v[6:7]
	v_or_b32_e32 v6, s55, v30
	v_lshlrev_b64 v[40:41], 12, v[6:7]
	v_lshl_add_u64 v[40:41], v[28:29], 0, v[40:41]
	v_lshl_add_u64 v[36:37], v[28:29], 0, v[36:37]
	v_lshl_add_u64 v[38:39], v[28:29], 0, v[38:39]
	global_load_dword v6, v[40:41], off
	global_load_dword v96, v[38:39], off
	global_load_dword v97, v[36:37], off
	global_load_dword v98, v[34:35], off
	v_or_b32_e32 v36, s27, v1
	v_or_b32_e32 v34, s39, v2
	s_add_i32 s23, s23, 16
	s_add_i32 s22, s22, 16
	s_add_i32 s26, s26, -16
	v_mad_u64_u32 v[34:35], s[40:41], v34, s25, v[4:5]
	v_mad_u64_u32 v[36:37], s[40:41], v36, s25, v[4:5]
	v_or_b32_e32 v35, s42, v1
	v_or_b32_e32 v37, s43, v2
	v_or_b32_e32 v44, s44, v1
	v_or_b32_e32 v42, s45, v2
	v_or_b32_e32 v68, s46, v1
	v_or_b32_e32 v66, s47, v2
	v_or_b32_e32 v72, s48, v1
	v_or_b32_e32 v70, s49, v2
	v_or_b32_e32 v76, s50, v1
	v_or_b32_e32 v74, s51, v2
	v_or_b32_e32 v80, s52, v1
	v_or_b32_e32 v78, s53, v2
	v_or_b32_e32 v84, s54, v1
	v_or_b32_e32 v82, s55, v2
	s_cmp_lg_u32 s26, 0
	v_mad_u64_u32 v[38:39], s[40:41], v37, s25, v[4:5]
	v_mad_u64_u32 v[40:41], s[40:41], v35, s25, v[4:5]
	v_mad_u64_u32 v[42:43], s[40:41], v42, s25, v[4:5]
	v_mad_u64_u32 v[44:45], s[40:41], v44, s25, v[4:5]
	v_mad_u64_u32 v[66:67], s[40:41], v66, s25, v[4:5]
	v_mad_u64_u32 v[68:69], s[40:41], v68, s25, v[4:5]
	v_mad_u64_u32 v[70:71], s[40:41], v70, s25, v[4:5]
	v_mad_u64_u32 v[72:73], s[40:41], v72, s25, v[4:5]
	v_mad_u64_u32 v[74:75], s[40:41], v74, s25, v[4:5]
	v_mad_u64_u32 v[76:77], s[40:41], v76, s25, v[4:5]
	v_mad_u64_u32 v[78:79], s[40:41], v78, s25, v[4:5]
	v_mad_u64_u32 v[80:81], s[40:41], v80, s25, v[4:5]
	v_mad_u64_u32 v[82:83], s[40:41], v82, s25, v[4:5]
	v_mad_u64_u32 v[84:85], s[40:41], v84, s25, v[4:5]
	s_waitcnt vmcnt(15)
	ds_write_b32 v34, v33
	s_waitcnt vmcnt(14)
	ds_write_b32 v36, v65
	s_waitcnt vmcnt(13)
	ds_write_b32 v38, v86
	s_waitcnt vmcnt(12)
	ds_write_b32 v40, v87
	s_waitcnt vmcnt(4)
	ds_write_b32 v42, v95
	ds_write_b32 v44, v88
	ds_write_b32 v66, v94
	ds_write_b32 v68, v89
	s_waitcnt vmcnt(0)
	ds_write_b32 v70, v98
	ds_write_b32 v72, v90
	ds_write_b32 v74, v97
	ds_write_b32 v76, v91
	ds_write_b32 v78, v96
	ds_write_b32 v80, v92
	ds_write_b32 v82, v6
	ds_write_b32 v84, v93
	s_cbranch_scc1 .Lmy_lt_103

	s_waitcnt lgkmcnt(0)
	ds_read2_b32 v[28:29], v48 offset1:33
	s_waitcnt lgkmcnt(0)
	v_cvt_pk_bf16_f32 v34, v28, v29
	ds_read2_b32 v[28:29], v48 offset0:66 offset1:99
	s_waitcnt lgkmcnt(0)
	v_cvt_pk_bf16_f32 v35, v28, v29
	ds_read2_b32 v[28:29], v48 offset0:132 offset1:165
	v_lshlrev_b32_e32 v6, 1, v32
	v_or_b32_e32 v3, v31, v47
	s_waitcnt lgkmcnt(0)
	v_cvt_pk_bf16_f32 v36, v28, v29
	ds_read2_b32 v[28:29], v48 offset0:198 offset1:231
	v_lshl_add_u64 v[38:39], v[14:15], 0, v[6:7]
	v_lshlrev_b32_e32 v6, 11, v3
	s_waitcnt lgkmcnt(0)
	v_cvt_pk_bf16_f32 v37, v28, v29
	ds_read2_b32 v[28:29], v48 offset0:8 offset1:41
	v_lshl_add_u64 v[32:33], v[38:39], 0, v[6:7]
	global_store_dwordx4 v[32:33], v[34:37], off
	s_waitcnt lgkmcnt(0)
	v_cvt_pk_bf16_f32 v32, v28, v29
	ds_read2_b32 v[28:29], v48 offset0:74 offset1:107
	s_waitcnt lgkmcnt(0)
	v_cvt_pk_bf16_f32 v33, v28, v29
	ds_read2_b32 v[28:29], v48 offset0:140 offset1:173
	v_or_b32_e32 v3, v31, v49
	s_waitcnt lgkmcnt(0)
	v_cvt_pk_bf16_f32 v34, v28, v29
	ds_read2_b32 v[28:29], v48 offset0:206 offset1:239
	v_lshlrev_b32_e32 v6, 11, v3
	s_waitcnt lgkmcnt(0)
	v_cvt_pk_bf16_f32 v35, v28, v29
	ds_read2_b32 v[28:29], v48 offset0:16 offset1:49
	v_lshl_add_u64 v[36:37], v[38:39], 0, v[6:7]
	global_store_dwordx4 v[36:37], v[32:35], off
	v_or_b32_e32 v3, v31, v50
	v_lshlrev_b32_e32 v6, 11, v3
	s_waitcnt lgkmcnt(0)
	v_cvt_pk_bf16_f32 v32, v28, v29
	ds_read2_b32 v[28:29], v48 offset0:82 offset1:115
	s_waitcnt lgkmcnt(0)
	v_cvt_pk_bf16_f32 v33, v28, v29
	ds_read2_b32 v[28:29], v48 offset0:148 offset1:181
	s_waitcnt lgkmcnt(0)
	v_cvt_pk_bf16_f32 v34, v28, v29
	ds_read2_b32 v[28:29], v48 offset0:214 offset1:247
	s_waitcnt lgkmcnt(0)
	v_cvt_pk_bf16_f32 v35, v28, v29
	ds_read2_b32 v[28:29], v48 offset0:24 offset1:57
	v_lshl_add_u64 v[36:37], v[38:39], 0, v[6:7]
	global_store_dwordx4 v[36:37], v[32:35], off
	s_waitcnt lgkmcnt(0)
	v_cvt_pk_bf16_f32 v28, v28, v29
	ds_read2_b32 v[32:33], v48 offset0:90 offset1:123
	s_waitcnt lgkmcnt(0)
	v_cvt_pk_bf16_f32 v29, v32, v33
	ds_read2_b32 v[32:33], v48 offset0:156 offset1:189
	v_or_b32_e32 v3, v31, v51
	s_waitcnt lgkmcnt(0)
	v_cvt_pk_bf16_f32 v30, v32, v33
	ds_read2_b32 v[32:33], v48 offset0:222 offset1:255
	v_lshlrev_b32_e32 v6, 11, v3
	s_waitcnt lgkmcnt(0)
	v_cvt_pk_bf16_f32 v31, v32, v33
	v_lshl_add_u64 v[32:33], v[38:39], 0, v[6:7]
	global_store_dwordx4 v[32:33], v[28:31], off
	s_waitcnt lgkmcnt(0)

.Lmy_lt_106:
	s_andn2_saveexec_b64 s[18:19], s[18:19]
	s_cbranch_execz .Lmy_lt_110

	v_add_u32_e32 v3, 0xfffff470, v5
	v_lshlrev_b32_e32 v6, 1, v3
	v_lshlrev_b32_e32 v3, 5, v3
	v_and_b32_e32 v31, 0x3e0, v3
	v_or_b32_e32 v3, v31, v46
	v_readlane_b32 s40, v253, 38
	v_and_b32_e32 v32, 0x1c0, v6
	v_lshlrev_b32_e32 v6, 2, v3
	v_readlane_b32 s54, v253, 52
	v_readlane_b32 s55, v253, 53
	s_mov_b32 s20, 1
	v_or_b32_e32 v3, v1, v32
	v_lshl_add_u64 v[28:29], s[54:55], 0, v[6:7]
	v_or_b32_e32 v30, v2, v32
	s_mov_b32 s21, 0
	s_mov_b32 s22, 32
	v_readlane_b32 s41, v253, 39
	v_readlane_b32 s42, v253, 40
	v_readlane_b32 s43, v253, 41
	v_readlane_b32 s44, v253, 42
	v_readlane_b32 s45, v253, 43
	v_readlane_b32 s46, v253, 44
	v_readlane_b32 s47, v253, 45
	v_readlane_b32 s48, v253, 46
	v_readlane_b32 s49, v253, 47
	v_readlane_b32 s50, v253, 48
	v_readlane_b32 s51, v253, 49
	v_readlane_b32 s52, v253, 50
	v_readlane_b32 s53, v253, 51
.Lmy_lt_108:

	s_lshl_b32 s26, s21, 1
	s_lshl_b32 s23, s20, 1
	v_or_b32_e32 v6, s26, v30
	s_add_i32 s40, s26, 4
	s_add_i32 s39, s23, 4
	s_add_i32 s41, s23, 8
	s_add_i32 s42, s26, 8
	v_lshlrev_b64 v[70:71], 12, v[6:7]
	v_or_b32_e32 v6, s40, v30
	v_mov_b32_e32 v35, v7
	v_mov_b32_e32 v37, v7
	v_mov_b32_e32 v39, v7
	v_or_b32_e32 v34, s23, v3
	s_add_i32 s43, s23, 12
	s_add_i32 s44, s26, 12
	s_add_i32 s45, s23, 16
	s_add_i32 s47, s23, 20
	s_add_i32 s49, s23, 24
	s_add_i32 s51, s23, 28
	v_or_b32_e32 v36, s39, v3
	v_or_b32_e32 v38, s41, v3
	v_lshlrev_b64 v[72:73], 12, v[6:7]
	v_or_b32_e32 v6, s42, v30
	v_mov_b32_e32 v41, v7
	v_mov_b32_e32 v43, v7
	v_mov_b32_e32 v45, v7
	v_mov_b32_e32 v67, v7
	v_mov_b32_e32 v69, v7
	s_add_i32 s46, s26, 16
	v_lshlrev_b64 v[34:35], 12, v[34:35]
	v_or_b32_e32 v40, s43, v3
	v_or_b32_e32 v42, s45, v3
	v_or_b32_e32 v44, s47, v3
	v_or_b32_e32 v66, s49, v3
	v_or_b32_e32 v68, s51, v3
	v_lshl_add_u64 v[70:71], v[28:29], 0, v[70:71]
	v_lshlrev_b64 v[36:37], 12, v[36:37]
	v_lshlrev_b64 v[38:39], 12, v[38:39]
	v_lshlrev_b64 v[74:75], 12, v[6:7]
	v_or_b32_e32 v6, s44, v30
	s_add_i32 s48, s26, 20
	v_lshl_add_u64 v[34:35], v[28:29], 0, v[34:35]
	v_lshlrev_b64 v[40:41], 12, v[40:41]
	v_lshlrev_b64 v[42:43], 12, v[42:43]
	v_lshlrev_b64 v[44:45], 12, v[44:45]
	v_lshlrev_b64 v[66:67], 12, v[66:67]
	v_lshlrev_b64 v[68:69], 12, v[68:69]
	v_lshl_add_u64 v[72:73], v[28:29], 0, v[72:73]
	v_lshl_add_u64 v[36:37], v[28:29], 0, v[36:37]
	v_lshl_add_u64 v[38:39], v[28:29], 0, v[38:39]
	global_load_dword v33, v[70:71], off
	global_load_dword v65, v[34:35], off
	v_lshlrev_b64 v[70:71], 12, v[6:7]
	v_or_b32_e32 v6, s46, v30
	s_add_i32 s50, s26, 24
	v_lshl_add_u64 v[40:41], v[28:29], 0, v[40:41]
	v_lshl_add_u64 v[42:43], v[28:29], 0, v[42:43]
	v_lshl_add_u64 v[44:45], v[28:29], 0, v[44:45]
	v_lshl_add_u64 v[66:67], v[28:29], 0, v[66:67]
	v_lshl_add_u64 v[68:69], v[28:29], 0, v[68:69]
	global_load_dword v86, v[72:73], off
	global_load_dword v87, v[36:37], off
	global_load_dword v88, v[38:39], off
	global_load_dword v89, v[40:41], off
	global_load_dword v90, v[42:43], off
	global_load_dword v91, v[44:45], off
	global_load_dword v92, v[66:67], off
	global_load_dword v93, v[68:69], off
	v_lshl_add_u64 v[36:37], v[28:29], 0, v[70:71]
	v_lshlrev_b64 v[38:39], 12, v[6:7]
	v_or_b32_e32 v6, s48, v30
	s_add_i32 s52, s26, 28
	v_lshl_add_u64 v[34:35], v[28:29], 0, v[74:75]
	global_load_dword v94, v[36:37], off
	global_load_dword v95, v[34:35], off
	v_lshlrev_b64 v[36:37], 12, v[6:7]
	v_or_b32_e32 v6, s50, v30
	v_lshl_add_u64 v[34:35], v[28:29], 0, v[38:39]
	v_lshlrev_b64 v[38:39], 12, v[6:7]
	v_or_b32_e32 v6, s52, v30
	v_lshlrev_b64 v[40:41], 12, v[6:7]
	v_lshl_add_u64 v[40:41], v[28:29], 0, v[40:41]
	v_lshl_add_u64 v[36:37], v[28:29], 0, v[36:37]
	v_lshl_add_u64 v[38:39], v[28:29], 0, v[38:39]
	global_load_dword v6, v[40:41], off
	global_load_dword v96, v[38:39], off
	global_load_dword v97, v[36:37], off
	global_load_dword v98, v[34:35], off
	v_or_b32_e32 v36, s23, v1
	v_or_b32_e32 v34, s26, v2
	s_add_i32 s21, s21, 16
	s_add_i32 s20, s20, 16
	s_add_i32 s22, s22, -16
	v_mad_u64_u32 v[34:35], s[26:27], v34, s25, v[4:5]
	v_mad_u64_u32 v[36:37], s[26:27], v36, s25, v[4:5]
	v_or_b32_e32 v35, s39, v1
	v_or_b32_e32 v37, s40, v2
	v_or_b32_e32 v44, s41, v1
	v_or_b32_e32 v42, s42, v2
	v_or_b32_e32 v68, s43, v1
	v_or_b32_e32 v66, s44, v2
	v_or_b32_e32 v72, s45, v1
	v_or_b32_e32 v70, s46, v2
	v_or_b32_e32 v76, s47, v1
	v_or_b32_e32 v74, s48, v2
	v_or_b32_e32 v80, s49, v1
	v_or_b32_e32 v78, s50, v2
	v_or_b32_e32 v84, s51, v1
	v_or_b32_e32 v82, s52, v2
	s_cmp_lg_u32 s22, 0
	v_mad_u64_u32 v[38:39], s[26:27], v37, s25, v[4:5]
	v_mad_u64_u32 v[40:41], s[26:27], v35, s25, v[4:5]
	v_mad_u64_u32 v[42:43], s[26:27], v42, s25, v[4:5]
	v_mad_u64_u32 v[44:45], s[26:27], v44, s25, v[4:5]
	v_mad_u64_u32 v[66:67], s[26:27], v66, s25, v[4:5]
	v_mad_u64_u32 v[68:69], s[26:27], v68, s25, v[4:5]
	v_mad_u64_u32 v[70:71], s[26:27], v70, s25, v[4:5]
	v_mad_u64_u32 v[72:73], s[26:27], v72, s25, v[4:5]
	v_mad_u64_u32 v[74:75], s[26:27], v74, s25, v[4:5]
	v_mad_u64_u32 v[76:77], s[26:27], v76, s25, v[4:5]
	v_mad_u64_u32 v[78:79], s[26:27], v78, s25, v[4:5]
	v_mad_u64_u32 v[80:81], s[26:27], v80, s25, v[4:5]
	v_mad_u64_u32 v[82:83], s[26:27], v82, s25, v[4:5]
	v_mad_u64_u32 v[84:85], s[26:27], v84, s25, v[4:5]
	s_waitcnt vmcnt(15)
	ds_write_b32 v34, v33
	s_waitcnt vmcnt(14)
	ds_write_b32 v36, v65
	s_waitcnt vmcnt(13)
	ds_write_b32 v38, v86
	s_waitcnt vmcnt(12)
	ds_write_b32 v40, v87
	s_waitcnt vmcnt(4)
	ds_write_b32 v42, v95
	ds_write_b32 v44, v88
	ds_write_b32 v66, v94
	ds_write_b32 v68, v89
	s_waitcnt vmcnt(0)
	ds_write_b32 v70, v98
	ds_write_b32 v72, v90
	ds_write_b32 v74, v97
	ds_write_b32 v76, v91
	ds_write_b32 v78, v96
	ds_write_b32 v80, v92
	ds_write_b32 v82, v6
	ds_write_b32 v84, v93
	s_cbranch_scc1 .Lmy_lt_108

	s_waitcnt lgkmcnt(0)
	ds_read2_b32 v[28:29], v48 offset1:33
	s_waitcnt lgkmcnt(0)
	v_cvt_pk_bf16_f32 v34, v28, v29
	ds_read2_b32 v[28:29], v48 offset0:66 offset1:99
	s_waitcnt lgkmcnt(0)
	v_cvt_pk_bf16_f32 v35, v28, v29
	ds_read2_b32 v[28:29], v48 offset0:132 offset1:165
	v_lshlrev_b32_e32 v6, 1, v32
	v_or_b32_e32 v3, v31, v47
	s_waitcnt lgkmcnt(0)
	v_cvt_pk_bf16_f32 v36, v28, v29
	ds_read2_b32 v[28:29], v48 offset0:198 offset1:231
	v_lshl_add_u64 v[38:39], v[16:17], 0, v[6:7]
	v_lshlrev_b32_e32 v6, 10, v3
	s_waitcnt lgkmcnt(0)
	v_cvt_pk_bf16_f32 v37, v28, v29
	ds_read2_b32 v[28:29], v48 offset0:8 offset1:41
	v_lshl_add_u64 v[32:33], v[38:39], 0, v[6:7]
	global_store_dwordx4 v[32:33], v[34:37], off
	s_waitcnt lgkmcnt(0)
	v_cvt_pk_bf16_f32 v32, v28, v29
	ds_read2_b32 v[28:29], v48 offset0:74 offset1:107
	s_waitcnt lgkmcnt(0)
	v_cvt_pk_bf16_f32 v33, v28, v29
	ds_read2_b32 v[28:29], v48 offset0:140 offset1:173
	v_or_b32_e32 v3, v31, v49
	s_waitcnt lgkmcnt(0)
	v_cvt_pk_bf16_f32 v34, v28, v29
	ds_read2_b32 v[28:29], v48 offset0:206 offset1:239
	v_lshlrev_b32_e32 v6, 10, v3
	s_waitcnt lgkmcnt(0)
	v_cvt_pk_bf16_f32 v35, v28, v29
	ds_read2_b32 v[28:29], v48 offset0:16 offset1:49
	v_lshl_add_u64 v[36:37], v[38:39], 0, v[6:7]
	global_store_dwordx4 v[36:37], v[32:35], off
	v_or_b32_e32 v3, v31, v50
	v_lshlrev_b32_e32 v6, 10, v3
	s_waitcnt lgkmcnt(0)
	v_cvt_pk_bf16_f32 v32, v28, v29
	ds_read2_b32 v[28:29], v48 offset0:82 offset1:115
	s_waitcnt lgkmcnt(0)
	v_cvt_pk_bf16_f32 v33, v28, v29
	ds_read2_b32 v[28:29], v48 offset0:148 offset1:181
	s_waitcnt lgkmcnt(0)
	v_cvt_pk_bf16_f32 v34, v28, v29
	ds_read2_b32 v[28:29], v48 offset0:214 offset1:247
	s_waitcnt lgkmcnt(0)
	v_cvt_pk_bf16_f32 v35, v28, v29
	ds_read2_b32 v[28:29], v48 offset0:24 offset1:57
	v_lshl_add_u64 v[36:37], v[38:39], 0, v[6:7]
	global_store_dwordx4 v[36:37], v[32:35], off
	s_waitcnt lgkmcnt(0)
	v_cvt_pk_bf16_f32 v28, v28, v29
	ds_read2_b32 v[32:33], v48 offset0:90 offset1:123
	s_waitcnt lgkmcnt(0)
	v_cvt_pk_bf16_f32 v29, v32, v33
	ds_read2_b32 v[32:33], v48 offset0:156 offset1:189
	v_or_b32_e32 v3, v31, v51
	s_waitcnt lgkmcnt(0)
	v_cvt_pk_bf16_f32 v30, v32, v33
	ds_read2_b32 v[32:33], v48 offset0:222 offset1:255
	v_lshlrev_b32_e32 v6, 10, v3
	s_waitcnt lgkmcnt(0)
	v_cvt_pk_bf16_f32 v31, v32, v33
	v_lshl_add_u64 v[32:33], v[38:39], 0, v[6:7]
	global_store_dwordx4 v[32:33], v[28:31], off
	s_waitcnt lgkmcnt(0)

.Lmy_lt_111:
	s_andn2_saveexec_b64 s[16:17], s[16:17]
	s_cbranch_execz .Lmy_lt_115

	v_add_u32_e32 v3, 0xfffff570, v5
	v_lshlrev_b32_e32 v6, 1, v3
	v_lshlrev_b32_e32 v3, 5, v3
	v_and_b32_e32 v31, 0x3e0, v3
	v_or_b32_e32 v3, v31, v46
	v_readlane_b32 s40, v253, 38
	v_and_b32_e32 v32, 0x1c0, v6
	v_lshlrev_b32_e32 v6, 2, v3
	v_readlane_b32 s50, v253, 48
	v_readlane_b32 s51, v253, 49
	s_mov_b32 s18, 1
	v_or_b32_e32 v3, v1, v32
	v_lshl_add_u64 v[28:29], s[50:51], 0, v[6:7]
	v_or_b32_e32 v30, v2, v32
	s_mov_b32 s19, 0
	s_mov_b32 s20, 32
	v_readlane_b32 s41, v253, 39
	v_readlane_b32 s42, v253, 40
	v_readlane_b32 s43, v253, 41
	v_readlane_b32 s44, v253, 42
	v_readlane_b32 s45, v253, 43
	v_readlane_b32 s46, v253, 44
	v_readlane_b32 s47, v253, 45
	v_readlane_b32 s48, v253, 46
	v_readlane_b32 s49, v253, 47
	v_readlane_b32 s52, v253, 50
	v_readlane_b32 s53, v253, 51
	v_readlane_b32 s54, v253, 52
	v_readlane_b32 s55, v253, 53
.Lmy_lt_113:

	s_lshl_b32 s22, s19, 1
	s_lshl_b32 s21, s18, 1
	v_or_b32_e32 v6, s22, v30
	s_add_i32 s27, s22, 4
	s_add_i32 s26, s21, 4
	s_add_i32 s39, s21, 8
	s_add_i32 s40, s22, 8
	v_lshlrev_b64 v[70:71], 12, v[6:7]
	v_or_b32_e32 v6, s27, v30
	v_mov_b32_e32 v35, v7
	v_mov_b32_e32 v37, v7
	v_mov_b32_e32 v39, v7
	v_or_b32_e32 v34, s21, v3
	s_add_i32 s41, s21, 12
	s_add_i32 s42, s22, 12
	s_add_i32 s43, s21, 16
	s_add_i32 s45, s21, 20
	s_add_i32 s47, s21, 24
	s_add_i32 s49, s21, 28
	v_or_b32_e32 v36, s26, v3
	v_or_b32_e32 v38, s39, v3
	v_lshlrev_b64 v[72:73], 12, v[6:7]
	v_or_b32_e32 v6, s40, v30
	v_mov_b32_e32 v41, v7
	v_mov_b32_e32 v43, v7
	v_mov_b32_e32 v45, v7
	v_mov_b32_e32 v67, v7
	v_mov_b32_e32 v69, v7
	s_add_i32 s44, s22, 16
	v_lshlrev_b64 v[34:35], 12, v[34:35]
	v_or_b32_e32 v40, s41, v3
	v_or_b32_e32 v42, s43, v3
	v_or_b32_e32 v44, s45, v3
	v_or_b32_e32 v66, s47, v3
	v_or_b32_e32 v68, s49, v3
	v_lshl_add_u64 v[70:71], v[28:29], 0, v[70:71]
	v_lshlrev_b64 v[36:37], 12, v[36:37]
	v_lshlrev_b64 v[38:39], 12, v[38:39]
	v_lshlrev_b64 v[74:75], 12, v[6:7]
	v_or_b32_e32 v6, s42, v30
	s_add_i32 s46, s22, 20
	v_lshl_add_u64 v[34:35], v[28:29], 0, v[34:35]
	v_lshlrev_b64 v[40:41], 12, v[40:41]
	v_lshlrev_b64 v[42:43], 12, v[42:43]
	v_lshlrev_b64 v[44:45], 12, v[44:45]
	v_lshlrev_b64 v[66:67], 12, v[66:67]
	v_lshlrev_b64 v[68:69], 12, v[68:69]
	v_lshl_add_u64 v[72:73], v[28:29], 0, v[72:73]
	v_lshl_add_u64 v[36:37], v[28:29], 0, v[36:37]
	v_lshl_add_u64 v[38:39], v[28:29], 0, v[38:39]
	global_load_dword v33, v[70:71], off
	global_load_dword v65, v[34:35], off
	v_lshlrev_b64 v[70:71], 12, v[6:7]
	v_or_b32_e32 v6, s44, v30
	s_add_i32 s48, s22, 24
	v_lshl_add_u64 v[40:41], v[28:29], 0, v[40:41]
	v_lshl_add_u64 v[42:43], v[28:29], 0, v[42:43]
	v_lshl_add_u64 v[44:45], v[28:29], 0, v[44:45]
	v_lshl_add_u64 v[66:67], v[28:29], 0, v[66:67]
	v_lshl_add_u64 v[68:69], v[28:29], 0, v[68:69]
	global_load_dword v86, v[72:73], off
	global_load_dword v87, v[36:37], off
	global_load_dword v88, v[38:39], off
	global_load_dword v89, v[40:41], off
	global_load_dword v90, v[42:43], off
	global_load_dword v91, v[44:45], off
	global_load_dword v92, v[66:67], off
	global_load_dword v93, v[68:69], off
	v_lshl_add_u64 v[36:37], v[28:29], 0, v[70:71]
	v_lshlrev_b64 v[38:39], 12, v[6:7]
	v_or_b32_e32 v6, s46, v30
	s_add_i32 s50, s22, 28
	v_lshl_add_u64 v[34:35], v[28:29], 0, v[74:75]
	global_load_dword v94, v[36:37], off
	global_load_dword v95, v[34:35], off
	v_lshlrev_b64 v[36:37], 12, v[6:7]
	v_or_b32_e32 v6, s48, v30
	v_lshl_add_u64 v[34:35], v[28:29], 0, v[38:39]
	v_lshlrev_b64 v[38:39], 12, v[6:7]
	v_or_b32_e32 v6, s50, v30
	v_lshlrev_b64 v[40:41], 12, v[6:7]
	v_lshl_add_u64 v[40:41], v[28:29], 0, v[40:41]
	v_lshl_add_u64 v[36:37], v[28:29], 0, v[36:37]
	v_lshl_add_u64 v[38:39], v[28:29], 0, v[38:39]
	global_load_dword v6, v[40:41], off
	global_load_dword v96, v[38:39], off
	global_load_dword v97, v[36:37], off
	global_load_dword v98, v[34:35], off
	v_or_b32_e32 v36, s21, v1
	v_or_b32_e32 v34, s22, v2
	s_add_i32 s19, s19, 16
	s_add_i32 s18, s18, 16
	s_add_i32 s20, s20, -16
	v_mad_u64_u32 v[34:35], s[22:23], v34, s25, v[4:5]
	v_mad_u64_u32 v[36:37], s[22:23], v36, s25, v[4:5]
	v_or_b32_e32 v35, s26, v1
	v_or_b32_e32 v37, s27, v2
	v_or_b32_e32 v44, s39, v1
	v_or_b32_e32 v42, s40, v2
	v_or_b32_e32 v68, s41, v1
	v_or_b32_e32 v66, s42, v2
	v_or_b32_e32 v72, s43, v1
	v_or_b32_e32 v70, s44, v2
	v_or_b32_e32 v76, s45, v1
	v_or_b32_e32 v74, s46, v2
	v_or_b32_e32 v80, s47, v1
	v_or_b32_e32 v78, s48, v2
	v_or_b32_e32 v84, s49, v1
	v_or_b32_e32 v82, s50, v2
	s_cmp_lg_u32 s20, 0
	v_mad_u64_u32 v[38:39], s[22:23], v37, s25, v[4:5]
	v_mad_u64_u32 v[40:41], s[22:23], v35, s25, v[4:5]
	v_mad_u64_u32 v[42:43], s[22:23], v42, s25, v[4:5]
	v_mad_u64_u32 v[44:45], s[22:23], v44, s25, v[4:5]
	v_mad_u64_u32 v[66:67], s[22:23], v66, s25, v[4:5]
	v_mad_u64_u32 v[68:69], s[22:23], v68, s25, v[4:5]
	v_mad_u64_u32 v[70:71], s[22:23], v70, s25, v[4:5]
	v_mad_u64_u32 v[72:73], s[22:23], v72, s25, v[4:5]
	v_mad_u64_u32 v[74:75], s[22:23], v74, s25, v[4:5]
	v_mad_u64_u32 v[76:77], s[22:23], v76, s25, v[4:5]
	v_mad_u64_u32 v[78:79], s[22:23], v78, s25, v[4:5]
	v_mad_u64_u32 v[80:81], s[22:23], v80, s25, v[4:5]
	v_mad_u64_u32 v[82:83], s[22:23], v82, s25, v[4:5]
	v_mad_u64_u32 v[84:85], s[22:23], v84, s25, v[4:5]
	s_waitcnt vmcnt(15)
	ds_write_b32 v34, v33
	s_waitcnt vmcnt(14)
	ds_write_b32 v36, v65
	s_waitcnt vmcnt(13)
	ds_write_b32 v38, v86
	s_waitcnt vmcnt(12)
	ds_write_b32 v40, v87
	s_waitcnt vmcnt(4)
	ds_write_b32 v42, v95
	ds_write_b32 v44, v88
	ds_write_b32 v66, v94
	ds_write_b32 v68, v89
	s_waitcnt vmcnt(0)
	ds_write_b32 v70, v98
	ds_write_b32 v72, v90
	ds_write_b32 v74, v97
	ds_write_b32 v76, v91
	ds_write_b32 v78, v96
	ds_write_b32 v80, v92
	ds_write_b32 v82, v6
	ds_write_b32 v84, v93
	s_cbranch_scc1 .Lmy_lt_113

	s_waitcnt lgkmcnt(0)
	ds_read2_b32 v[28:29], v48 offset1:33
	s_waitcnt lgkmcnt(0)
	v_cvt_pk_bf16_f32 v34, v28, v29
	ds_read2_b32 v[28:29], v48 offset0:66 offset1:99
	s_waitcnt lgkmcnt(0)
	v_cvt_pk_bf16_f32 v35, v28, v29
	ds_read2_b32 v[28:29], v48 offset0:132 offset1:165
	v_lshlrev_b32_e32 v6, 1, v32
	v_or_b32_e32 v3, v31, v47
	s_waitcnt lgkmcnt(0)
	v_cvt_pk_bf16_f32 v36, v28, v29
	ds_read2_b32 v[28:29], v48 offset0:198 offset1:231
	v_lshl_add_u64 v[38:39], v[18:19], 0, v[6:7]
	v_lshlrev_b32_e32 v6, 10, v3
	s_waitcnt lgkmcnt(0)
	v_cvt_pk_bf16_f32 v37, v28, v29
	ds_read2_b32 v[28:29], v48 offset0:8 offset1:41
	v_lshl_add_u64 v[32:33], v[38:39], 0, v[6:7]
	global_store_dwordx4 v[32:33], v[34:37], off
	s_waitcnt lgkmcnt(0)
	v_cvt_pk_bf16_f32 v32, v28, v29
	ds_read2_b32 v[28:29], v48 offset0:74 offset1:107
	s_waitcnt lgkmcnt(0)
	v_cvt_pk_bf16_f32 v33, v28, v29
	ds_read2_b32 v[28:29], v48 offset0:140 offset1:173
	v_or_b32_e32 v3, v31, v49
	s_waitcnt lgkmcnt(0)
	v_cvt_pk_bf16_f32 v34, v28, v29
	ds_read2_b32 v[28:29], v48 offset0:206 offset1:239
	v_lshlrev_b32_e32 v6, 10, v3
	s_waitcnt lgkmcnt(0)
	v_cvt_pk_bf16_f32 v35, v28, v29
	ds_read2_b32 v[28:29], v48 offset0:16 offset1:49
	v_lshl_add_u64 v[36:37], v[38:39], 0, v[6:7]
	global_store_dwordx4 v[36:37], v[32:35], off
	v_or_b32_e32 v3, v31, v50
	v_lshlrev_b32_e32 v6, 10, v3
	s_waitcnt lgkmcnt(0)
	v_cvt_pk_bf16_f32 v32, v28, v29
	ds_read2_b32 v[28:29], v48 offset0:82 offset1:115
	s_waitcnt lgkmcnt(0)
	v_cvt_pk_bf16_f32 v33, v28, v29
	ds_read2_b32 v[28:29], v48 offset0:148 offset1:181
	s_waitcnt lgkmcnt(0)
	v_cvt_pk_bf16_f32 v34, v28, v29
	ds_read2_b32 v[28:29], v48 offset0:214 offset1:247
	s_waitcnt lgkmcnt(0)
	v_cvt_pk_bf16_f32 v35, v28, v29
	ds_read2_b32 v[28:29], v48 offset0:24 offset1:57
	v_lshl_add_u64 v[36:37], v[38:39], 0, v[6:7]
	global_store_dwordx4 v[36:37], v[32:35], off
	s_waitcnt lgkmcnt(0)
	v_cvt_pk_bf16_f32 v28, v28, v29
	ds_read2_b32 v[32:33], v48 offset0:90 offset1:123
	s_waitcnt lgkmcnt(0)
	v_cvt_pk_bf16_f32 v29, v32, v33
	ds_read2_b32 v[32:33], v48 offset0:156 offset1:189
	v_or_b32_e32 v3, v31, v51
	s_waitcnt lgkmcnt(0)
	v_cvt_pk_bf16_f32 v30, v32, v33
	ds_read2_b32 v[32:33], v48 offset0:222 offset1:255
	v_lshlrev_b32_e32 v6, 10, v3
	s_waitcnt lgkmcnt(0)
	v_cvt_pk_bf16_f32 v31, v32, v33
	v_lshl_add_u64 v[32:33], v[38:39], 0, v[6:7]
	global_store_dwordx4 v[32:33], v[28:31], off
	s_waitcnt lgkmcnt(0)

.Lmy_lt_116:
	s_andn2_saveexec_b64 s[14:15], s[14:15]
	s_cbranch_execz .Lmy_lt_120

	v_and_b32_e32 v3, 15, v5
	v_lshl_add_u32 v6, v5, 2, v61
	v_lshlrev_b32_e32 v31, 5, v3
	v_and_b32_e32 v32, 0x3c0, v6
	v_lshlrev_b32_e32 v3, 6, v3
	v_and_b32_e32 v6, 32, v31
	v_or3_b32 v3, v6, v3, v52
	v_readlane_b32 s40, v253, 38
	v_lshlrev_b32_e32 v6, 2, v3
	v_readlane_b32 s48, v253, 46
	v_readlane_b32 s49, v253, 47
	s_mov_b32 s16, 32
	v_or_b32_e32 v3, v1, v32
	v_lshl_add_u64 v[28:29], s[48:49], 0, v[6:7]
	v_or_b32_e32 v30, v2, v32
	s_mov_b32 s17, 1
	s_mov_b32 s18, 0
	v_readlane_b32 s41, v253, 39
	v_readlane_b32 s42, v253, 40
	v_readlane_b32 s43, v253, 41
	v_readlane_b32 s44, v253, 42
	v_readlane_b32 s45, v253, 43
	v_readlane_b32 s46, v253, 44
	v_readlane_b32 s47, v253, 45
	v_readlane_b32 s50, v253, 48
	v_readlane_b32 s51, v253, 49
	v_readlane_b32 s52, v253, 50
	v_readlane_b32 s53, v253, 51
	v_readlane_b32 s54, v253, 52
	v_readlane_b32 s55, v253, 53
.Lmy_lt_118:

	s_lshl_b32 s20, s18, 1
	s_lshl_b32 s19, s17, 1
	v_or_b32_e32 v6, s20, v30
	s_add_i32 s23, s20, 4
	s_add_i32 s22, s19, 4
	s_add_i32 s26, s19, 8
	s_add_i32 s27, s20, 8
	v_lshlrev_b64 v[70:71], 12, v[6:7]
	v_or_b32_e32 v6, s23, v30
	v_mov_b32_e32 v35, v7
	v_mov_b32_e32 v37, v7
	v_mov_b32_e32 v39, v7
	v_or_b32_e32 v34, s19, v3
	s_add_i32 s39, s19, 12
	s_add_i32 s40, s20, 12
	s_add_i32 s41, s19, 16
	s_add_i32 s43, s19, 20
	s_add_i32 s45, s19, 24
	s_add_i32 s47, s19, 28
	v_or_b32_e32 v36, s22, v3
	v_or_b32_e32 v38, s26, v3
	v_lshlrev_b64 v[72:73], 12, v[6:7]
	v_or_b32_e32 v6, s27, v30
	v_mov_b32_e32 v41, v7
	v_mov_b32_e32 v43, v7
	v_mov_b32_e32 v45, v7
	v_mov_b32_e32 v67, v7
	v_mov_b32_e32 v69, v7
	s_add_i32 s42, s20, 16
	v_lshlrev_b64 v[34:35], 12, v[34:35]
	v_or_b32_e32 v40, s39, v3
	v_or_b32_e32 v42, s41, v3
	v_or_b32_e32 v44, s43, v3
	v_or_b32_e32 v66, s45, v3
	v_or_b32_e32 v68, s47, v3
	v_lshl_add_u64 v[70:71], v[28:29], 0, v[70:71]
	v_lshlrev_b64 v[36:37], 12, v[36:37]
	v_lshlrev_b64 v[38:39], 12, v[38:39]
	v_lshlrev_b64 v[74:75], 12, v[6:7]
	v_or_b32_e32 v6, s40, v30
	s_add_i32 s44, s20, 20
	v_lshl_add_u64 v[34:35], v[28:29], 0, v[34:35]
	v_lshlrev_b64 v[40:41], 12, v[40:41]
	v_lshlrev_b64 v[42:43], 12, v[42:43]
	v_lshlrev_b64 v[44:45], 12, v[44:45]
	v_lshlrev_b64 v[66:67], 12, v[66:67]
	v_lshlrev_b64 v[68:69], 12, v[68:69]
	v_lshl_add_u64 v[72:73], v[28:29], 0, v[72:73]
	v_lshl_add_u64 v[36:37], v[28:29], 0, v[36:37]
	v_lshl_add_u64 v[38:39], v[28:29], 0, v[38:39]
	global_load_dword v33, v[70:71], off
	global_load_dword v65, v[34:35], off
	v_lshlrev_b64 v[70:71], 12, v[6:7]
	v_or_b32_e32 v6, s42, v30
	s_add_i32 s46, s20, 24
	v_lshl_add_u64 v[40:41], v[28:29], 0, v[40:41]
	v_lshl_add_u64 v[42:43], v[28:29], 0, v[42:43]
	v_lshl_add_u64 v[44:45], v[28:29], 0, v[44:45]
	v_lshl_add_u64 v[66:67], v[28:29], 0, v[66:67]
	v_lshl_add_u64 v[68:69], v[28:29], 0, v[68:69]
	global_load_dword v86, v[72:73], off
	global_load_dword v87, v[36:37], off
	global_load_dword v88, v[38:39], off
	global_load_dword v89, v[40:41], off
	global_load_dword v90, v[42:43], off
	global_load_dword v91, v[44:45], off
	global_load_dword v92, v[66:67], off
	global_load_dword v93, v[68:69], off
	v_lshl_add_u64 v[36:37], v[28:29], 0, v[70:71]
	v_lshlrev_b64 v[38:39], 12, v[6:7]
	v_or_b32_e32 v6, s44, v30
	s_add_i32 s48, s20, 28
	v_lshl_add_u64 v[34:35], v[28:29], 0, v[74:75]
	global_load_dword v94, v[36:37], off
	global_load_dword v95, v[34:35], off
	v_lshlrev_b64 v[36:37], 12, v[6:7]
	v_or_b32_e32 v6, s46, v30
	v_lshl_add_u64 v[34:35], v[28:29], 0, v[38:39]
	v_lshlrev_b64 v[38:39], 12, v[6:7]
	v_or_b32_e32 v6, s48, v30
	v_lshlrev_b64 v[40:41], 12, v[6:7]
	v_lshl_add_u64 v[40:41], v[28:29], 0, v[40:41]
	v_lshl_add_u64 v[36:37], v[28:29], 0, v[36:37]
	v_lshl_add_u64 v[38:39], v[28:29], 0, v[38:39]
	global_load_dword v6, v[40:41], off
	global_load_dword v96, v[38:39], off
	global_load_dword v97, v[36:37], off
	global_load_dword v98, v[34:35], off
	v_or_b32_e32 v36, s19, v1
	v_or_b32_e32 v34, s20, v2
	s_add_i32 s18, s18, 16
	s_add_i32 s17, s17, 16
	s_add_i32 s16, s16, -16
	v_mad_u64_u32 v[34:35], s[20:21], v34, s25, v[4:5]
	v_mad_u64_u32 v[36:37], s[20:21], v36, s25, v[4:5]
	v_or_b32_e32 v35, s22, v1
	v_or_b32_e32 v37, s23, v2
	v_or_b32_e32 v44, s26, v1
	v_or_b32_e32 v42, s27, v2
	v_or_b32_e32 v68, s39, v1
	v_or_b32_e32 v66, s40, v2
	v_or_b32_e32 v72, s41, v1
	v_or_b32_e32 v70, s42, v2
	v_or_b32_e32 v76, s43, v1
	v_or_b32_e32 v74, s44, v2
	v_or_b32_e32 v80, s45, v1
	v_or_b32_e32 v78, s46, v2
	v_or_b32_e32 v84, s47, v1
	v_or_b32_e32 v82, s48, v2
	s_cmp_lg_u32 s16, 0
	v_mad_u64_u32 v[38:39], s[20:21], v37, s25, v[4:5]
	v_mad_u64_u32 v[40:41], s[20:21], v35, s25, v[4:5]
	v_mad_u64_u32 v[42:43], s[20:21], v42, s25, v[4:5]
	v_mad_u64_u32 v[44:45], s[20:21], v44, s25, v[4:5]
	v_mad_u64_u32 v[66:67], s[20:21], v66, s25, v[4:5]
	v_mad_u64_u32 v[68:69], s[20:21], v68, s25, v[4:5]
	v_mad_u64_u32 v[70:71], s[20:21], v70, s25, v[4:5]
	v_mad_u64_u32 v[72:73], s[20:21], v72, s25, v[4:5]
	v_mad_u64_u32 v[74:75], s[20:21], v74, s25, v[4:5]
	v_mad_u64_u32 v[76:77], s[20:21], v76, s25, v[4:5]
	v_mad_u64_u32 v[78:79], s[20:21], v78, s25, v[4:5]
	v_mad_u64_u32 v[80:81], s[20:21], v80, s25, v[4:5]
	v_mad_u64_u32 v[82:83], s[20:21], v82, s25, v[4:5]
	v_mad_u64_u32 v[84:85], s[20:21], v84, s25, v[4:5]
	s_waitcnt vmcnt(15)
	ds_write_b32 v34, v33
	s_waitcnt vmcnt(14)
	ds_write_b32 v36, v65
	s_waitcnt vmcnt(13)
	ds_write_b32 v38, v86
	s_waitcnt vmcnt(12)
	ds_write_b32 v40, v87
	s_waitcnt vmcnt(4)
	ds_write_b32 v42, v95
	ds_write_b32 v44, v88
	ds_write_b32 v66, v94
	ds_write_b32 v68, v89
	s_waitcnt vmcnt(0)
	ds_write_b32 v70, v98
	ds_write_b32 v72, v90
	ds_write_b32 v74, v97
	ds_write_b32 v76, v91
	ds_write_b32 v78, v96
	ds_write_b32 v80, v92
	ds_write_b32 v82, v6
	ds_write_b32 v84, v93
	s_cbranch_scc1 .Lmy_lt_118

	s_waitcnt lgkmcnt(0)
	ds_read2_b32 v[28:29], v48 offset1:33
	s_waitcnt lgkmcnt(0)
	v_cvt_pk_bf16_f32 v34, v28, v29
	ds_read2_b32 v[28:29], v48 offset0:66 offset1:99
	s_waitcnt lgkmcnt(0)
	v_cvt_pk_bf16_f32 v35, v28, v29
	ds_read2_b32 v[28:29], v48 offset0:132 offset1:165
	v_lshlrev_b32_e32 v6, 1, v32
	v_or_b32_e32 v3, v31, v47
	s_waitcnt lgkmcnt(0)
	v_cvt_pk_bf16_f32 v36, v28, v29
	ds_read2_b32 v[28:29], v48 offset0:198 offset1:231
	v_lshl_add_u64 v[38:39], v[20:21], 0, v[6:7]
	v_lshlrev_b32_e32 v6, 9, v3
	s_waitcnt lgkmcnt(0)
	v_cvt_pk_bf16_f32 v37, v28, v29
	ds_read2_b32 v[28:29], v48 offset0:8 offset1:41
	v_lshl_add_u64 v[32:33], v[38:39], 0, v[6:7]
	global_store_dwordx4 v[32:33], v[34:37], off
	s_waitcnt lgkmcnt(0)
	v_cvt_pk_bf16_f32 v32, v28, v29
	ds_read2_b32 v[28:29], v48 offset0:74 offset1:107
	s_waitcnt lgkmcnt(0)
	v_cvt_pk_bf16_f32 v33, v28, v29
	ds_read2_b32 v[28:29], v48 offset0:140 offset1:173
	v_or_b32_e32 v3, v31, v49
	s_waitcnt lgkmcnt(0)
	v_cvt_pk_bf16_f32 v34, v28, v29
	ds_read2_b32 v[28:29], v48 offset0:206 offset1:239
	v_lshlrev_b32_e32 v6, 9, v3
	s_waitcnt lgkmcnt(0)
	v_cvt_pk_bf16_f32 v35, v28, v29
	ds_read2_b32 v[28:29], v48 offset0:16 offset1:49
	v_lshl_add_u64 v[36:37], v[38:39], 0, v[6:7]
	global_store_dwordx4 v[36:37], v[32:35], off
	v_or_b32_e32 v3, v31, v50
	v_lshlrev_b32_e32 v6, 9, v3
	s_waitcnt lgkmcnt(0)
	v_cvt_pk_bf16_f32 v32, v28, v29
	ds_read2_b32 v[28:29], v48 offset0:82 offset1:115
	s_waitcnt lgkmcnt(0)
	v_cvt_pk_bf16_f32 v33, v28, v29
	ds_read2_b32 v[28:29], v48 offset0:148 offset1:181
	s_waitcnt lgkmcnt(0)
	v_cvt_pk_bf16_f32 v34, v28, v29
	ds_read2_b32 v[28:29], v48 offset0:214 offset1:247
	s_waitcnt lgkmcnt(0)
	v_cvt_pk_bf16_f32 v35, v28, v29
	ds_read2_b32 v[28:29], v48 offset0:24 offset1:57
	v_lshl_add_u64 v[36:37], v[38:39], 0, v[6:7]
	global_store_dwordx4 v[36:37], v[32:35], off
	s_waitcnt lgkmcnt(0)
	v_cvt_pk_bf16_f32 v28, v28, v29
	ds_read2_b32 v[32:33], v48 offset0:90 offset1:123
	s_waitcnt lgkmcnt(0)
	v_cvt_pk_bf16_f32 v29, v32, v33
	ds_read2_b32 v[32:33], v48 offset0:156 offset1:189
	v_or_b32_e32 v3, v31, v51
	s_waitcnt lgkmcnt(0)
	v_cvt_pk_bf16_f32 v30, v32, v33
	ds_read2_b32 v[32:33], v48 offset0:222 offset1:255
	v_lshlrev_b32_e32 v6, 9, v3
	s_waitcnt lgkmcnt(0)
	v_cvt_pk_bf16_f32 v31, v32, v33
	v_lshl_add_u64 v[32:33], v[38:39], 0, v[6:7]
	global_store_dwordx4 v[32:33], v[28:31], off
	s_waitcnt lgkmcnt(0)

.Lmy_lt_121:
	s_andn2_saveexec_b64 s[12:13], s[12:13]
	s_cbranch_execz .Lmy_lt_125

	v_lshl_add_u32 v3, v5, 2, v62
	v_and_b32_e32 v31, 0x3c0, v3
	v_lshlrev_b32_e32 v32, 5, v5
	v_lshlrev_b32_e32 v3, 6, v5
	v_and_b32_e32 v3, 0x380, v3
	v_and_b32_e32 v6, 32, v32
	v_or3_b32 v3, v6, v3, v46
	v_readlane_b32 s40, v253, 38
	v_lshlrev_b32_e32 v6, 2, v3
	v_readlane_b32 s48, v253, 46
	v_readlane_b32 s49, v253, 47
	s_mov_b32 s14, 32
	v_or_b32_e32 v3, v1, v31
	v_lshl_add_u64 v[28:29], s[48:49], 0, v[6:7]
	v_or_b32_e32 v30, v2, v31
	s_mov_b32 s15, 1
	s_mov_b32 s16, 0
	v_readlane_b32 s41, v253, 39
	v_readlane_b32 s42, v253, 40
	v_readlane_b32 s43, v253, 41
	v_readlane_b32 s44, v253, 42
	v_readlane_b32 s45, v253, 43
	v_readlane_b32 s46, v253, 44
	v_readlane_b32 s47, v253, 45
	v_readlane_b32 s50, v253, 48
	v_readlane_b32 s51, v253, 49
	v_readlane_b32 s52, v253, 50
	v_readlane_b32 s53, v253, 51
	v_readlane_b32 s54, v253, 52
	v_readlane_b32 s55, v253, 53
.Lmy_lt_123:

	s_lshl_b32 s18, s16, 1
	s_lshl_b32 s17, s15, 1
	v_or_b32_e32 v6, s18, v30
	s_add_i32 s21, s18, 4
	s_add_i32 s20, s17, 4
	s_add_i32 s22, s17, 8
	s_add_i32 s23, s18, 8
	v_lshlrev_b64 v[70:71], 12, v[6:7]
	v_or_b32_e32 v6, s21, v30
	v_mov_b32_e32 v35, v7
	v_mov_b32_e32 v37, v7
	v_mov_b32_e32 v39, v7
	v_or_b32_e32 v34, s17, v3
	s_add_i32 s26, s17, 12
	s_add_i32 s27, s18, 12
	s_add_i32 s39, s17, 16
	s_add_i32 s41, s17, 20
	s_add_i32 s43, s17, 24
	s_add_i32 s45, s17, 28
	v_or_b32_e32 v36, s20, v3
	v_or_b32_e32 v38, s22, v3
	v_lshlrev_b64 v[72:73], 12, v[6:7]
	v_or_b32_e32 v6, s23, v30
	v_mov_b32_e32 v41, v7
	v_mov_b32_e32 v43, v7
	v_mov_b32_e32 v45, v7
	v_mov_b32_e32 v67, v7
	v_mov_b32_e32 v69, v7
	s_add_i32 s40, s18, 16
	v_lshlrev_b64 v[34:35], 12, v[34:35]
	v_or_b32_e32 v40, s26, v3
	v_or_b32_e32 v42, s39, v3
	v_or_b32_e32 v44, s41, v3
	v_or_b32_e32 v66, s43, v3
	v_or_b32_e32 v68, s45, v3
	v_lshl_add_u64 v[70:71], v[28:29], 0, v[70:71]
	v_lshlrev_b64 v[36:37], 12, v[36:37]
	v_lshlrev_b64 v[38:39], 12, v[38:39]
	v_lshlrev_b64 v[74:75], 12, v[6:7]
	v_or_b32_e32 v6, s27, v30
	s_add_i32 s42, s18, 20
	v_lshl_add_u64 v[34:35], v[28:29], 0, v[34:35]
	v_lshlrev_b64 v[40:41], 12, v[40:41]
	v_lshlrev_b64 v[42:43], 12, v[42:43]
	v_lshlrev_b64 v[44:45], 12, v[44:45]
	v_lshlrev_b64 v[66:67], 12, v[66:67]
	v_lshlrev_b64 v[68:69], 12, v[68:69]
	v_lshl_add_u64 v[72:73], v[28:29], 0, v[72:73]
	v_lshl_add_u64 v[36:37], v[28:29], 0, v[36:37]
	v_lshl_add_u64 v[38:39], v[28:29], 0, v[38:39]
	global_load_dword v33, v[70:71], off
	global_load_dword v65, v[34:35], off
	v_lshlrev_b64 v[70:71], 12, v[6:7]
	v_or_b32_e32 v6, s40, v30
	s_add_i32 s44, s18, 24
	v_lshl_add_u64 v[40:41], v[28:29], 0, v[40:41]
	v_lshl_add_u64 v[42:43], v[28:29], 0, v[42:43]
	v_lshl_add_u64 v[44:45], v[28:29], 0, v[44:45]
	v_lshl_add_u64 v[66:67], v[28:29], 0, v[66:67]
	v_lshl_add_u64 v[68:69], v[28:29], 0, v[68:69]
	global_load_dword v86, v[72:73], off
	global_load_dword v87, v[36:37], off
	global_load_dword v88, v[38:39], off
	global_load_dword v89, v[40:41], off
	global_load_dword v90, v[42:43], off
	global_load_dword v91, v[44:45], off
	global_load_dword v92, v[66:67], off
	global_load_dword v93, v[68:69], off
	v_lshl_add_u64 v[36:37], v[28:29], 0, v[70:71]
	v_lshlrev_b64 v[38:39], 12, v[6:7]
	v_or_b32_e32 v6, s42, v30
	s_add_i32 s46, s18, 28
	v_lshl_add_u64 v[34:35], v[28:29], 0, v[74:75]
	global_load_dword v94, v[36:37], off
	global_load_dword v95, v[34:35], off
	v_lshlrev_b64 v[36:37], 12, v[6:7]
	v_or_b32_e32 v6, s44, v30
	v_lshl_add_u64 v[34:35], v[28:29], 0, v[38:39]
	v_lshlrev_b64 v[38:39], 12, v[6:7]
	v_or_b32_e32 v6, s46, v30
	v_lshlrev_b64 v[40:41], 12, v[6:7]
	v_lshl_add_u64 v[40:41], v[28:29], 0, v[40:41]
	v_lshl_add_u64 v[36:37], v[28:29], 0, v[36:37]
	v_lshl_add_u64 v[38:39], v[28:29], 0, v[38:39]
	global_load_dword v6, v[40:41], off
	global_load_dword v96, v[38:39], off
	global_load_dword v97, v[36:37], off
	global_load_dword v98, v[34:35], off
	v_or_b32_e32 v36, s17, v1
	v_or_b32_e32 v34, s18, v2
	s_add_i32 s16, s16, 16
	s_add_i32 s15, s15, 16
	s_add_i32 s14, s14, -16
	v_mad_u64_u32 v[34:35], s[18:19], v34, s25, v[4:5]
	v_mad_u64_u32 v[36:37], s[18:19], v36, s25, v[4:5]
	v_or_b32_e32 v35, s20, v1
	v_or_b32_e32 v37, s21, v2
	v_or_b32_e32 v44, s22, v1
	v_or_b32_e32 v42, s23, v2
	v_or_b32_e32 v68, s26, v1
	v_or_b32_e32 v66, s27, v2
	v_or_b32_e32 v72, s39, v1
	v_or_b32_e32 v70, s40, v2
	v_or_b32_e32 v76, s41, v1
	v_or_b32_e32 v74, s42, v2
	v_or_b32_e32 v80, s43, v1
	v_or_b32_e32 v78, s44, v2
	v_or_b32_e32 v84, s45, v1
	v_or_b32_e32 v82, s46, v2
	s_cmp_lg_u32 s14, 0
	v_mad_u64_u32 v[38:39], s[18:19], v37, s25, v[4:5]
	v_mad_u64_u32 v[40:41], s[18:19], v35, s25, v[4:5]
	v_mad_u64_u32 v[42:43], s[18:19], v42, s25, v[4:5]
	v_mad_u64_u32 v[44:45], s[18:19], v44, s25, v[4:5]
	v_mad_u64_u32 v[66:67], s[18:19], v66, s25, v[4:5]
	v_mad_u64_u32 v[68:69], s[18:19], v68, s25, v[4:5]
	v_mad_u64_u32 v[70:71], s[18:19], v70, s25, v[4:5]
	v_mad_u64_u32 v[72:73], s[18:19], v72, s25, v[4:5]
	v_mad_u64_u32 v[74:75], s[18:19], v74, s25, v[4:5]
	v_mad_u64_u32 v[76:77], s[18:19], v76, s25, v[4:5]
	v_mad_u64_u32 v[78:79], s[18:19], v78, s25, v[4:5]
	v_mad_u64_u32 v[80:81], s[18:19], v80, s25, v[4:5]
	v_mad_u64_u32 v[82:83], s[18:19], v82, s25, v[4:5]
	v_mad_u64_u32 v[84:85], s[18:19], v84, s25, v[4:5]
	s_waitcnt vmcnt(15)
	ds_write_b32 v34, v33
	s_waitcnt vmcnt(14)
	ds_write_b32 v36, v65
	s_waitcnt vmcnt(13)
	ds_write_b32 v38, v86
	s_waitcnt vmcnt(12)
	ds_write_b32 v40, v87
	s_waitcnt vmcnt(4)
	ds_write_b32 v42, v95
	ds_write_b32 v44, v88
	ds_write_b32 v66, v94
	ds_write_b32 v68, v89
	s_waitcnt vmcnt(0)
	ds_write_b32 v70, v98
	ds_write_b32 v72, v90
	ds_write_b32 v74, v97
	ds_write_b32 v76, v91
	ds_write_b32 v78, v96
	ds_write_b32 v80, v92
	ds_write_b32 v82, v6
	ds_write_b32 v84, v93
	s_cbranch_scc1 .Lmy_lt_123

	s_waitcnt lgkmcnt(0)
	ds_read2_b32 v[28:29], v48 offset1:33
	v_and_b32_e32 v3, 0x1e0, v32
	v_lshlrev_b32_e32 v6, 1, v31
	s_waitcnt lgkmcnt(0)
	v_cvt_pk_bf16_f32 v28, v28, v29
	ds_read2_b32 v[34:35], v48 offset0:66 offset1:99
	v_lshl_add_u64 v[32:33], v[22:23], 0, v[6:7]
	v_or_b32_e32 v6, v3, v47
	s_waitcnt lgkmcnt(0)
	v_cvt_pk_bf16_f32 v29, v34, v35
	ds_read2_b32 v[34:35], v48 offset0:132 offset1:165
	v_lshlrev_b32_e32 v6, 9, v6
	s_waitcnt lgkmcnt(0)
	v_cvt_pk_bf16_f32 v30, v34, v35
	ds_read2_b32 v[34:35], v48 offset0:198 offset1:231
	s_waitcnt lgkmcnt(0)
	v_cvt_pk_bf16_f32 v31, v34, v35
	v_lshl_add_u64 v[36:37], v[32:33], 0, v[6:7]
	ds_read2_b32 v[34:35], v48 offset0:8 offset1:41
	global_store_dwordx4 v[36:37], v[28:31], off
	v_or_b32_e32 v6, v3, v49
	v_lshlrev_b32_e32 v6, 9, v6
	s_waitcnt lgkmcnt(0)
	v_cvt_pk_bf16_f32 v28, v34, v35
	ds_read2_b32 v[30:31], v48 offset0:74 offset1:107
	s_waitcnt lgkmcnt(0)
	v_cvt_pk_bf16_f32 v29, v30, v31
	ds_read2_b32 v[30:31], v48 offset0:140 offset1:173
	s_waitcnt lgkmcnt(0)
	v_cvt_pk_bf16_f32 v30, v30, v31
	ds_read2_b32 v[34:35], v48 offset0:206 offset1:239
	s_waitcnt lgkmcnt(0)
	v_cvt_pk_bf16_f32 v31, v34, v35
	v_lshl_add_u64 v[36:37], v[32:33], 0, v[6:7]
	ds_read2_b32 v[34:35], v48 offset0:16 offset1:49
	global_store_dwordx4 v[36:37], v[28:31], off
	v_or_b32_e32 v6, v3, v50
	v_lshlrev_b32_e32 v6, 9, v6
	s_waitcnt lgkmcnt(0)
	v_cvt_pk_bf16_f32 v28, v34, v35
	ds_read2_b32 v[30:31], v48 offset0:82 offset1:115
	s_waitcnt lgkmcnt(0)
	v_cvt_pk_bf16_f32 v29, v30, v31
	ds_read2_b32 v[30:31], v48 offset0:148 offset1:181
	s_waitcnt lgkmcnt(0)
	v_cvt_pk_bf16_f32 v30, v30, v31
	ds_read2_b32 v[34:35], v48 offset0:214 offset1:247
	s_waitcnt lgkmcnt(0)
	v_cvt_pk_bf16_f32 v31, v34, v35
	v_lshl_add_u64 v[36:37], v[32:33], 0, v[6:7]
	v_or_b32_e32 v3, v3, v51
	ds_read2_b32 v[34:35], v48 offset0:24 offset1:57
	global_store_dwordx4 v[36:37], v[28:31], off
	v_lshlrev_b32_e32 v6, 9, v3
	v_lshl_add_u64 v[32:33], v[32:33], 0, v[6:7]
	s_waitcnt lgkmcnt(0)
	v_cvt_pk_bf16_f32 v28, v34, v35
	ds_read2_b32 v[30:31], v48 offset0:90 offset1:123
	s_waitcnt lgkmcnt(0)
	v_cvt_pk_bf16_f32 v29, v30, v31
	ds_read2_b32 v[30:31], v48 offset0:156 offset1:189
	s_waitcnt lgkmcnt(0)
	v_cvt_pk_bf16_f32 v30, v30, v31
	ds_read2_b32 v[34:35], v48 offset0:222 offset1:255
	s_waitcnt lgkmcnt(0)
	v_cvt_pk_bf16_f32 v31, v34, v35
	global_store_dwordx4 v[32:33], v[28:31], off
	s_waitcnt lgkmcnt(0)

.Lmy_lt_126:
	s_andn2_saveexec_b64 s[10:11], s[10:11]
	s_cbranch_execz .Lmy_lt_130

	s_movk_i32 s12, 0xff
	v_bitop3_b16 v6, v5, s12, v63 bitop3:0x48
	v_mul_lo_u16_e32 v6, 0xab, v6
	v_lshrrev_b16_e32 v6, 12, v6
	v_xor_b32_e32 v3, 0xffffff80, v5
	v_mul_lo_u16_e32 v28, 24, v6
	v_sub_u16_e32 v3, v3, v28
	v_lshlrev_b32_sdwa v30, v64, v3 dst_sel:DWORD dst_unused:UNUSED_PAD src0_sel:DWORD src1_sel:BYTE_0
	v_or_b32_e32 v3, v30, v46
	v_readlane_b32 s40, v253, 38
	v_lshlrev_b32_e32 v31, 6, v6
	v_lshlrev_b32_e32 v6, 2, v3
	v_readlane_b32 s46, v253, 44
	v_readlane_b32 s47, v253, 45
	v_or_b32_e32 v3, v1, v31
	s_mov_b32 s12, 1
	v_lshl_add_u64 v[28:29], s[46:47], 0, v[6:7]
	v_or_b32_e32 v6, v2, v31
	s_mov_b32 s13, 0
	s_mov_b32 s14, 32
	v_readlane_b32 s41, v253, 39
	v_readlane_b32 s42, v253, 40
	v_readlane_b32 s43, v253, 41
	v_readlane_b32 s44, v253, 42
	v_readlane_b32 s45, v253, 43
	v_readlane_b32 s48, v253, 46
	v_readlane_b32 s49, v253, 47
	v_readlane_b32 s50, v253, 48
	v_readlane_b32 s51, v253, 49
	v_readlane_b32 s52, v253, 50
	v_readlane_b32 s53, v253, 51
	v_readlane_b32 s54, v253, 52
	v_readlane_b32 s55, v253, 53
.Lmy_lt_128:

	s_lshl_b32 s15, s12, 1
	s_lshl_b32 s18, s13, 1
	v_or_b32_e32 v32, s18, v6
	s_add_i32 s19, s15, 4
	s_add_i32 s20, s18, 4
	s_add_i32 s21, s15, 8
	s_add_i32 s22, s18, 8
	s_add_i32 s23, s15, 12
	s_add_i32 s26, s18, 12
	s_add_i32 s27, s15, 16
	s_add_i32 s39, s18, 16
	s_add_i32 s40, s15, 20
	s_add_i32 s41, s18, 20
	s_add_i32 s42, s15, 24
	s_add_i32 s43, s18, 24
	s_add_i32 s44, s15, 28
	s_add_i32 s45, s18, 28
	v_or_b32_e32 v34, s15, v3
	v_mad_u64_u32 v[32:33], s[16:17], v32, s37, v[28:29]
	v_or_b32_e32 v38, s19, v3
	v_or_b32_e32 v36, s20, v6
	v_or_b32_e32 v42, s21, v3
	v_or_b32_e32 v40, s22, v6
	v_or_b32_e32 v65, s23, v3
	v_or_b32_e32 v44, s26, v6
	v_or_b32_e32 v70, s27, v3
	v_or_b32_e32 v68, s39, v6
	v_or_b32_e32 v74, s40, v3
	v_or_b32_e32 v72, s41, v6
	v_or_b32_e32 v78, s42, v3
	v_or_b32_e32 v76, s43, v6
	v_or_b32_e32 v82, s44, v3
	v_or_b32_e32 v80, s45, v6
	v_mad_u64_u32 v[34:35], s[16:17], v34, s37, v[28:29]
	v_mad_u64_u32 v[36:37], s[16:17], v36, s37, v[28:29]
	v_mad_u64_u32 v[38:39], s[16:17], v38, s37, v[28:29]
	v_mad_u64_u32 v[40:41], s[16:17], v40, s37, v[28:29]
	v_mad_u64_u32 v[42:43], s[16:17], v42, s37, v[28:29]
	v_mad_u64_u32 v[44:45], s[16:17], v44, s37, v[28:29]
	v_mad_u64_u32 v[66:67], s[16:17], v65, s37, v[28:29]
	v_mad_u64_u32 v[68:69], s[16:17], v68, s37, v[28:29]
	v_mad_u64_u32 v[70:71], s[16:17], v70, s37, v[28:29]
	v_mad_u64_u32 v[72:73], s[16:17], v72, s37, v[28:29]
	v_mad_u64_u32 v[74:75], s[16:17], v74, s37, v[28:29]
	v_mad_u64_u32 v[76:77], s[16:17], v76, s37, v[28:29]
	v_mad_u64_u32 v[78:79], s[16:17], v78, s37, v[28:29]
	v_mad_u64_u32 v[80:81], s[16:17], v80, s37, v[28:29]
	v_mad_u64_u32 v[82:83], s[16:17], v82, s37, v[28:29]
	global_load_dword v65, v[32:33], off
	global_load_dword v84, v[34:35], off
	global_load_dword v85, v[36:37], off
	global_load_dword v86, v[38:39], off
	global_load_dword v87, v[40:41], off
	global_load_dword v88, v[42:43], off
	global_load_dword v89, v[44:45], off
	global_load_dword v90, v[66:67], off
	global_load_dword v91, v[68:69], off
	global_load_dword v92, v[70:71], off
	global_load_dword v93, v[72:73], off
	global_load_dword v94, v[74:75], off
	global_load_dword v95, v[76:77], off
	global_load_dword v96, v[78:79], off
	global_load_dword v97, v[80:81], off
	global_load_dword v98, v[82:83], off
	v_or_b32_e32 v34, s15, v1
	v_or_b32_e32 v32, s18, v2
	s_add_i32 s13, s13, 16
	s_add_i32 s12, s12, 16
	s_add_i32 s14, s14, -16
	v_mad_u64_u32 v[32:33], s[16:17], v32, s25, v[4:5]
	v_mad_u64_u32 v[34:35], s[16:17], v34, s25, v[4:5]
	v_or_b32_e32 v33, s19, v1
	v_or_b32_e32 v35, s20, v2
	v_or_b32_e32 v42, s21, v1
	v_or_b32_e32 v40, s22, v2
	v_or_b32_e32 v66, s23, v1
	v_or_b32_e32 v44, s26, v2
	v_or_b32_e32 v70, s27, v1
	v_or_b32_e32 v68, s39, v2
	v_or_b32_e32 v74, s40, v1
	v_or_b32_e32 v72, s41, v2
	v_or_b32_e32 v78, s42, v1
	v_or_b32_e32 v76, s43, v2
	v_or_b32_e32 v82, s44, v1
	v_or_b32_e32 v80, s45, v2
	s_cmp_lg_u32 s14, 0
	v_mad_u64_u32 v[36:37], s[16:17], v35, s25, v[4:5]
	v_mad_u64_u32 v[38:39], s[16:17], v33, s25, v[4:5]
	v_mad_u64_u32 v[40:41], s[16:17], v40, s25, v[4:5]
	v_mad_u64_u32 v[42:43], s[16:17], v42, s25, v[4:5]
	v_mad_u64_u32 v[44:45], s[16:17], v44, s25, v[4:5]
	v_mad_u64_u32 v[66:67], s[16:17], v66, s25, v[4:5]
	v_mad_u64_u32 v[68:69], s[16:17], v68, s25, v[4:5]
	v_mad_u64_u32 v[70:71], s[16:17], v70, s25, v[4:5]
	v_mad_u64_u32 v[72:73], s[16:17], v72, s25, v[4:5]
	v_mad_u64_u32 v[74:75], s[16:17], v74, s25, v[4:5]
	v_mad_u64_u32 v[76:77], s[16:17], v76, s25, v[4:5]
	v_mad_u64_u32 v[78:79], s[16:17], v78, s25, v[4:5]
	v_mad_u64_u32 v[80:81], s[16:17], v80, s25, v[4:5]
	v_mad_u64_u32 v[82:83], s[16:17], v82, s25, v[4:5]
	s_waitcnt vmcnt(15)
	ds_write_b32 v32, v65
	s_waitcnt vmcnt(14)
	ds_write_b32 v34, v84
	s_waitcnt vmcnt(13)
	ds_write_b32 v36, v85
	s_waitcnt vmcnt(12)
	ds_write_b32 v38, v86
	s_waitcnt vmcnt(11)
	ds_write_b32 v40, v87
	s_waitcnt vmcnt(10)
	ds_write_b32 v42, v88
	s_waitcnt vmcnt(9)
	ds_write_b32 v44, v89
	s_waitcnt vmcnt(8)
	ds_write_b32 v66, v90
	s_waitcnt vmcnt(7)
	ds_write_b32 v68, v91
	s_waitcnt vmcnt(6)
	ds_write_b32 v70, v92
	s_waitcnt vmcnt(5)
	ds_write_b32 v72, v93
	s_waitcnt vmcnt(4)
	ds_write_b32 v74, v94
	s_waitcnt vmcnt(3)
	ds_write_b32 v76, v95
	s_waitcnt vmcnt(2)
	ds_write_b32 v78, v96
	s_waitcnt vmcnt(1)
	ds_write_b32 v80, v97
	s_waitcnt vmcnt(0)
	ds_write_b32 v82, v98
	s_cbranch_scc1 .Lmy_lt_128

	s_waitcnt lgkmcnt(0)
	ds_read2_b32 v[28:29], v48 offset1:33
	s_waitcnt lgkmcnt(0)
	v_cvt_pk_bf16_f32 v32, v28, v29
	ds_read2_b32 v[28:29], v48 offset0:66 offset1:99
	v_or_b32_e32 v3, v30, v47
	s_waitcnt lgkmcnt(0)
	v_cvt_pk_bf16_f32 v33, v28, v29
	ds_read2_b32 v[28:29], v48 offset0:132 offset1:165
	v_lshlrev_b32_e32 v6, 1, v31
	v_mul_u32_u24_e32 v3, 0x180, v3
	s_waitcnt lgkmcnt(0)
	v_cvt_pk_bf16_f32 v34, v28, v29
	ds_read2_b32 v[28:29], v48 offset0:198 offset1:231
	v_lshl_add_u64 v[36:37], v[24:25], 0, v[6:7]
	v_lshlrev_b32_e32 v6, 1, v3
	s_waitcnt lgkmcnt(0)
	v_cvt_pk_bf16_f32 v35, v28, v29
	ds_read2_b32 v[28:29], v48 offset0:8 offset1:41
	v_lshl_add_u64 v[38:39], v[36:37], 0, v[6:7]
	global_store_dwordx4 v[38:39], v[32:35], off
	v_or_b32_e32 v3, v30, v49
	v_mul_u32_u24_e32 v3, 0x180, v3
	s_waitcnt lgkmcnt(0)
	v_cvt_pk_bf16_f32 v32, v28, v29
	ds_read2_b32 v[28:29], v48 offset0:74 offset1:107
	s_waitcnt lgkmcnt(0)
	v_cvt_pk_bf16_f32 v33, v28, v29
	ds_read2_b32 v[28:29], v48 offset0:140 offset1:173
	s_waitcnt lgkmcnt(0)
	v_cvt_pk_bf16_f32 v34, v28, v29
	ds_read2_b32 v[28:29], v48 offset0:206 offset1:239
	v_lshlrev_b32_e32 v6, 1, v3
	s_waitcnt lgkmcnt(0)
	v_cvt_pk_bf16_f32 v35, v28, v29
	ds_read2_b32 v[28:29], v48 offset0:16 offset1:49
	v_lshl_add_u64 v[38:39], v[36:37], 0, v[6:7]
	global_store_dwordx4 v[38:39], v[32:35], off
	v_or_b32_e32 v3, v30, v50
	v_mul_u32_u24_e32 v3, 0x180, v3
	s_waitcnt lgkmcnt(0)
	v_cvt_pk_bf16_f32 v32, v28, v29
	ds_read2_b32 v[28:29], v48 offset0:82 offset1:115
	s_waitcnt lgkmcnt(0)
	v_cvt_pk_bf16_f32 v33, v28, v29
	ds_read2_b32 v[28:29], v48 offset0:148 offset1:181
	s_waitcnt lgkmcnt(0)
	v_cvt_pk_bf16_f32 v34, v28, v29
	ds_read2_b32 v[28:29], v48 offset0:214 offset1:247
	v_lshlrev_b32_e32 v6, 1, v3
	s_waitcnt lgkmcnt(0)
	v_cvt_pk_bf16_f32 v35, v28, v29
	ds_read2_b32 v[28:29], v48 offset0:24 offset1:57
	v_lshl_add_u64 v[38:39], v[36:37], 0, v[6:7]
	global_store_dwordx4 v[38:39], v[32:35], off
	v_or_b32_e32 v3, v30, v51
	v_mul_u32_u24_e32 v3, 0x180, v3
	s_waitcnt lgkmcnt(0)
	v_cvt_pk_bf16_f32 v32, v28, v29
	ds_read2_b32 v[28:29], v48 offset0:90 offset1:123
	s_waitcnt lgkmcnt(0)
	v_cvt_pk_bf16_f32 v33, v28, v29
	ds_read2_b32 v[28:29], v48 offset0:156 offset1:189
	s_waitcnt lgkmcnt(0)
	v_cvt_pk_bf16_f32 v34, v28, v29
	ds_read2_b32 v[28:29], v48 offset0:222 offset1:255
	v_lshlrev_b32_e32 v6, 1, v3
	s_waitcnt lgkmcnt(0)
	v_cvt_pk_bf16_f32 v35, v28, v29
	v_lshl_add_u64 v[28:29], v[36:37], 0, v[6:7]
	global_store_dwordx4 v[28:29], v[32:35], off
	s_waitcnt lgkmcnt(0)

.Lmy_lt_131:
	s_andn2_saveexec_b64 s[8:9], s[8:9]
	s_cbranch_execz .Lmy_lt_78

	s_mov_b32 s10, 0x6bca1af3
	v_mul_hi_i32 v3, v5, s10
	v_lshrrev_b32_e32 v6, 31, v3
	v_ashrrev_i32_e32 v3, 6, v3
	v_add_u32_e32 v28, v3, v6
	s_movk_i32 s10, 0x98
	v_mul_lo_u32 v3, v28, s10
	v_sub_u32_e32 v3, v5, v3
	v_lshlrev_b32_e32 v3, 5, v3
	v_or_b32_e32 v6, v3, v46
	s_movk_i32 s10, 0x7ff
	v_cmp_lt_i32_e32 vcc, s10, v6
	s_and_saveexec_b64 s[10:11], vcc
	s_cbranch_execz .Lmy_lt_152

	v_cmp_lt_u32_e32 vcc, s36, v3
	s_and_saveexec_b64 s[12:13], vcc
	s_xor_b64 s[12:13], exec, s[12:13]
	s_cbranch_execz .Lmy_lt_149

	s_movk_i32 s14, 0x99f
	v_cmp_lt_u32_e32 vcc, s14, v3
	s_and_saveexec_b64 s[14:15], vcc
	s_xor_b64 s[14:15], exec, s[14:15]
	s_cbranch_execz .Lmy_lt_146

	s_movk_i32 s16, 0x9af
	v_cmp_lt_u32_e32 vcc, s16, v6
	s_and_saveexec_b64 s[16:17], vcc
	s_xor_b64 s[16:17], exec, s[16:17]
	s_cbranch_execz .Lmy_lt_143

	s_movk_i32 s18, 0x9ff
	v_cmp_lt_u32_e32 vcc, s18, v3
	v_mov_b32_e32 v29, -1
	s_and_saveexec_b64 s[18:19], vcc
	s_cbranch_execz .Lmy_lt_142

	s_movk_i32 s20, 0xaff
	v_cmp_lt_u32_e32 vcc, s20, v3
	s_and_saveexec_b64 s[20:21], vcc
	s_xor_b64 s[20:21], exec, s[20:21]

	v_add_u32_e32 v29, 0xffffffb0, v6

	s_andn2_saveexec_b64 s[20:21], s[20:21]

	v_add_u32_e32 v29, 0xffffff90, v6

	s_or_b64 exec, exec, s[20:21]

.Lmy_lt_143:
	s_andn2_saveexec_b64 s[16:17], s[16:17]

	v_add_u32_e32 v29, 0xfffffe60, v6

	s_or_b64 exec, exec, s[16:17]
.Lmy_lt_146:
	s_andn2_saveexec_b64 s[14:15], s[14:15]

	v_add_u32_e32 v29, 0x110, v6

	s_or_b64 exec, exec, s[14:15]
.Lmy_lt_149:
	s_andn2_saveexec_b64 s[12:13], s[12:13]

	v_add_u32_e32 v29, 16, v6

	s_or_b64 exec, exec, s[12:13]
	v_mov_b32_e32 v6, v29

.Lmy_lt_154:

	v_mov_b32_e32 v29, 0
	v_mov_b32_e32 v65, 0
	s_and_saveexec_b64 s[12:13], vcc
	s_cbranch_execz .Lmy_lt_156

	v_lshl_add_u64 v[66:67], v[44:45], 0, s[10:11]
	global_load_dword v65, v[66:67], off
.Lmy_lt_156:
	s_or_b64 exec, exec, s[12:13]
	s_waitcnt vmcnt(0)
	ds_write_b32 v6, v65
	s_and_saveexec_b64 s[12:13], vcc
	s_cbranch_execz .Lmy_lt_158

	v_lshl_add_u64 v[66:67], v[42:43], 0, s[10:11]
	global_load_dword v29, v[66:67], off
.Lmy_lt_158:
	s_or_b64 exec, exec, s[12:13]
	s_waitcnt vmcnt(0)
	ds_write_b32 v6, v29 offset:264
	v_mov_b32_e32 v29, 0
	v_mov_b32_e32 v65, 0
	s_and_saveexec_b64 s[12:13], vcc
	s_cbranch_execz .Lmy_lt_160

	v_lshl_add_u64 v[66:67], v[40:41], 0, s[10:11]
	global_load_dword v65, v[66:67], off
.Lmy_lt_160:
	s_or_b64 exec, exec, s[12:13]
	s_waitcnt vmcnt(0)
	ds_write_b32 v6, v65 offset:528
	s_and_saveexec_b64 s[12:13], vcc
	s_cbranch_execz .Lmy_lt_162

	v_lshl_add_u64 v[66:67], v[38:39], 0, s[10:11]
	global_load_dword v29, v[66:67], off
.Lmy_lt_162:
	s_or_b64 exec, exec, s[12:13]
	s_waitcnt vmcnt(0)
	ds_write_b32 v6, v29 offset:792
	v_mov_b32_e32 v29, 0
	v_mov_b32_e32 v65, 0
	s_and_saveexec_b64 s[12:13], vcc
	s_cbranch_execz .Lmy_lt_164

	v_lshl_add_u64 v[66:67], v[36:37], 0, s[10:11]
	global_load_dword v65, v[66:67], off
.Lmy_lt_164:
	s_or_b64 exec, exec, s[12:13]
	s_waitcnt vmcnt(0)
	ds_write_b32 v6, v65 offset:1056
	s_and_saveexec_b64 s[12:13], vcc
	s_cbranch_execz .Lmy_lt_166

	v_lshl_add_u64 v[66:67], v[34:35], 0, s[10:11]
	global_load_dword v29, v[66:67], off
.Lmy_lt_166:
	s_or_b64 exec, exec, s[12:13]
	s_waitcnt vmcnt(0)
	ds_write_b32 v6, v29 offset:1320
	v_mov_b32_e32 v29, 0
	v_mov_b32_e32 v65, 0
	s_and_saveexec_b64 s[12:13], vcc
	s_cbranch_execz .Lmy_lt_168

	v_lshl_add_u64 v[66:67], v[32:33], 0, s[10:11]
	global_load_dword v65, v[66:67], off
.Lmy_lt_168:
	s_or_b64 exec, exec, s[12:13]
	s_waitcnt vmcnt(0)
	ds_write_b32 v6, v65 offset:1584
	s_and_saveexec_b64 s[12:13], vcc
	s_cbranch_execz .Lmy_lt_153

	v_lshl_add_u64 v[66:67], v[30:31], 0, s[10:11]
	global_load_dword v29, v[66:67], off
	s_branch .Lmy_lt_153
.Lmy_lt_170:
	s_or_b64 exec, exec, s[0:1]
	s_waitcnt vmcnt(0) lgkmcnt(0)
.Lmy_lt_skip:
	s_cmp_lt_i32 s86, 3
	s_cselect_b64 s[8:9], -1, 0
.LBB0_672:
	s_cmp_gt_i32 s87, 3
	s_cselect_b64 s[0:1], -1, 0
	s_and_b64 s[2:3], s[8:9], s[0:1]
	s_andn2_b64 vcc, exec, s[2:3]
	s_cbranch_vccnz .LBB0_738
	s_cmp_lg_u32 s86, 1
	s_mov_b64 s[2:3], -1
	s_cbranch_scc0 .LBB0_723
	s_waitcnt vmcnt(0)
	v_cmp_eq_u32_e32 vcc, 0, v202
	s_barrier
	s_and_saveexec_b64 s[2:3], vcc
	s_cbranch_execz .LBB0_722
	s_add_i32 s4, 0, 0x23fc0
	v_mov_b32_e32 v1, s4
	s_waitcnt vmcnt(0) expcnt(0) lgkmcnt(0)
	ds_read_b32 v3, v1
	s_add_i32 s4, 0, 0x23fc4
	v_mov_b32_e32 v1, s4
	ds_read_b32 v1, v1
	s_waitcnt lgkmcnt(1)
	v_cmp_ne_u32_e32 vcc, 0, v3
	s_cbranch_vccnz .LBB0_690
	s_add_u32 s4, s84, 0x80200
	s_addc_u32 s5, s85, 0
	s_add_u32 s6, s84, 0x80400
	s_addc_u32 s7, s85, 0
	s_add_u32 s8, s84, 0x80500
	s_addc_u32 s9, s85, 0
	s_add_u32 s10, s84, 0x80600
	s_addc_u32 s11, s85, 0
	s_add_u32 s12, s84, 0x80700
	s_addc_u32 s13, s85, 0
	s_add_u32 s14, s84, 0x80800
	s_addc_u32 s15, s85, 0
	s_add_u32 s16, s84, 0x80900
	s_addc_u32 s17, s85, 0
	s_add_u32 s18, s84, 0x80a00
	s_addc_u32 s19, s85, 0
	s_add_u32 s20, s84, 0x80b00
	s_addc_u32 s21, s85, 0
	s_add_u32 s22, s84, 0x80c00
	s_addc_u32 s23, s85, 0
	s_add_u32 s26, s84, 0x80d00
	s_addc_u32 s27, s85, 0
	s_add_u32 s50, s84, 0x80e00
	s_addc_u32 s51, s85, 0
	s_add_u32 s52, s84, 0x80f00
	s_addc_u32 s53, s85, 0
	s_add_u32 s54, s84, 0x81000
	s_addc_u32 s55, s85, 0
	s_add_u32 s56, s84, 0x81100
	s_addc_u32 s57, s85, 0
	s_add_u32 s58, s84, 0x81200
	s_addc_u32 s59, s85, 0
	s_mul_i32 s24, s79, s33
	s_add_u32 s60, s84, 0x81300
	s_mul_i32 s24, s24, s78
	s_addc_u32 s61, s85, 0
	s_mov_b32 s25, 1
	v_mov_b32_e32 v17, 0
	s_branch .LBB0_678
